# v24 + agent-scope write-through (sc1) on phase 3c/4b/5/6 output stores to shrink barrier write-back
# baseline (speedup 1.0000x reference)
; __device__ __forceinline__ void phase3c(const Params& p) {
;     ...
;     for (int it = blockIdx.x; it < 32 * 64; it += gridDim.x) {
;         const int bh = it >> 6, c4 = it & 63, b = bh >> 3, h = bh & 7;
;         const int c = h * 64 + sub * 4;
;         const f32x4 gain = *(const f32x4*)(p.in[14] + c), bias = *(const f32x4*)(p.in[15] + c), rk = *(const f32x4*)(p.in[13] + c);
;         u32x2 yb2[U]; f32x4 y[U]; h16x4 r4[U], k4[U], v4[U]; u32x2 g2[U];
; #pragma unroll
;         for (int u = 0; u < U; ++u) {
;             const int t = NMETA + (c4 * U + u) * 32 + (tid >> 4);
;             const size_t base = ((size_t)bh * TP + t) * 64 + sub * 4;
;             const size_t rec = ((size_t)bh * TP + t) * 448, pbase = rec + (sub & 3) * 16 + (sub >> 2) * 4;
;             yb2[u] = *(const u32x2*)(Y + base);
;             r4[u] = *(const h16x4*)(SI + SI_R * 64 + pbase); k4[u] = *(const h16x4*)(SI + SI_K * 64 + pbase); v4[u] = *(const h16x4*)(SI + SI_V * 64 + rec + sub * 4);
;             g2[u] = *(const u32x2*)((const bf16_t*)SI + 6 * 64 + pbase);
;         }
.LBB0_953:
	s_and_b32 s4, s25, 0x1c0
	s_and_b32 s1, s20, 0x1f80
	s_ashr_i32 s0, s25, 6
	s_and_b32 s5, s17, 0xffffe000
	s_waitcnt vmcnt(0)
	v_or_b32_e32 v27, s4, v9
	v_or_b32_e32 v10, s1, v34
	v_or_b32_e32 v0, s5, v169
	v_lshlrev_b32_e32 v28, 2, v27
	v_mad_i64_i32 v[24:25], s[4:5], s0, v35, v[10:11]
	v_mov_b32_e32 v19, v11
	v_mov_b32_e32 v21, v11
	v_add_u32_e32 v18, 32, v10
	v_add_u32_e32 v20, 64, v10
	v_or_b32_e32 v26, s1, v0
	global_load_dwordx4 v[0:3], v28, s[84:85]
	global_load_dwordx4 v[4:7], v28, s[86:87]
	global_load_dwordx4 v[36:39], v28, s[82:83]
	v_mad_u64_u32 v[28:29], s[4:5], v24, s22, 0
	v_lshlrev_b64 v[30:31], 7, v[24:25]
	v_add_u32_e32 v10, 0x60, v10
	v_mad_i64_i32 v[32:33], s[4:5], s0, v35, v[18:19]
	v_mad_i64_i32 v[20:21], s[4:5], s0, v35, v[20:21]
	v_or_b32_e32 v42, 64, v26
	v_mov_b32_e32 v18, v29
	v_lshl_add_u64 v[30:31], v[12:13], 0, v[30:31]
	v_mad_i64_i32 v[40:41], s[0:1], s0, v35, v[10:11]
	v_lshlrev_b32_e32 v10, 1, v27
	v_add_u32_e32 v44, 0x60, v26
	v_mad_u64_u32 v[52:53], s[0:1], v20, s22, 0
	v_ashrrev_i32_e32 v43, 31, v42
	v_mad_u64_u32 v[24:25], s[0:1], v25, s22, v[18:19]
	global_load_dwordx2 v[30:31], v[30:31], off
	v_or_b32_e32 v46, v28, v8
	v_lshlrev_b64 v[54:55], 7, v[20:21]
	v_mad_u64_u32 v[56:57], s[0:1], v40, s22, 0
	v_lshl_add_u64 v[60:61], s[44:45], 0, v[10:11]
	v_ashrrev_i32_e32 v45, 31, v44
	v_mov_b32_e32 v20, v53
	v_lshlrev_b64 v[42:43], 10, v[42:43]
	v_mov_b32_e32 v47, v24
	v_mad_u64_u32 v[48:49], s[0:1], v32, s22, 0
	v_lshlrev_b64 v[50:51], 7, v[32:33]
	v_mov_b32_e32 v62, v57
	v_lshlrev_b64 v[44:45], 10, v[44:45]
	v_mad_u64_u32 v[68:69], s[0:1], v21, s22, v[20:21]
	v_lshl_add_u64 v[20:21], v[60:61], 0, v[42:43]
	v_lshlrev_b64 v[42:43], 1, v[46:47]
	v_mov_b32_e32 v10, v49
	v_lshl_add_u64 v[50:51], v[12:13], 0, v[50:51]
	v_mov_b32_e32 v29, v24
	v_mad_u64_u32 v[62:63], s[0:1], v41, s22, v[62:63]
	v_lshl_add_u64 v[24:25], v[60:61], 0, v[44:45]
	v_lshl_add_u64 v[44:45], s[8:9], 0, v[42:43]
	v_lshl_add_u64 v[46:47], s[10:11], 0, v[42:43]
	v_lshl_add_u64 v[42:43], s[14:15], 0, v[42:43]
	v_ashrrev_i32_e32 v27, 31, v26
	v_mad_u64_u32 v[66:67], s[0:1], v33, s22, v[10:11]
	v_lshl_add_u64 v[28:29], v[28:29], 1, v[14:15]
	v_mov_b32_e32 v57, v62
	v_mov_b32_e32 v65, v62
	global_load_dwordx2 v[44:45], v[44:45], off
	s_nop 0
	global_load_dwordx2 v[46:47], v[46:47], off
	s_nop 0
	global_load_dwordx2 v[42:43], v[42:43], off
	s_nop 0
	global_load_dwordx2 v[62:63], v[28:29], off
	s_nop 0
	global_load_dwordx2 v[50:51], v[50:51], off
	v_lshlrev_b64 v[58:59], 7, v[40:41]
	v_lshlrev_b64 v[26:27], 10, v[26:27]
	v_or_b32_e32 v32, v48, v8
	v_or_b32_e32 v40, v52, v8
	v_or_b32_e32 v64, v56, v8
	v_mov_b32_e32 v33, v66
	v_mov_b32_e32 v41, v68
	v_lshl_add_u64 v[18:19], v[60:61], 0, v[26:27]
	v_mov_b32_e32 v49, v66
	v_mov_b32_e32 v53, v68
	v_lshlrev_b64 v[32:33], 1, v[32:33]
	v_lshlrev_b64 v[40:41], 1, v[40:41]
	v_lshlrev_b64 v[60:61], 1, v[64:65]
	v_lshl_add_u64 v[54:55], v[12:13], 0, v[54:55]
	v_lshl_add_u64 v[58:59], v[12:13], 0, v[58:59]
	v_lshl_add_u64 v[48:49], v[48:49], 1, v[14:15]
	v_lshl_add_u64 v[52:53], v[52:53], 1, v[14:15]
	v_lshl_add_u64 v[56:57], v[56:57], 1, v[14:15]
	v_lshl_add_u64 v[28:29], s[8:9], 0, v[32:33]
	v_lshl_add_u64 v[64:65], s[10:11], 0, v[32:33]
	v_lshl_add_u64 v[66:67], s[8:9], 0, v[40:41]
	v_lshl_add_u64 v[68:69], s[10:11], 0, v[40:41]
	v_lshl_add_u64 v[40:41], s[14:15], 0, v[40:41]
	v_lshl_add_u64 v[70:71], s[8:9], 0, v[60:61]
	v_lshl_add_u64 v[72:73], s[10:11], 0, v[60:61]
	v_lshl_add_u64 v[60:61], s[14:15], 0, v[60:61]
	global_load_dwordx2 v[48:49], v[48:49], off
	v_lshl_add_u64 v[32:33], s[14:15], 0, v[32:33]
	global_load_dwordx2 v[74:75], v[28:29], off
	s_nop 0
	global_load_dwordx2 v[64:65], v[64:65], off
	s_nop 0
	global_load_dwordx2 v[76:77], v[32:33], off
	s_nop 0
	global_load_dwordx2 v[54:55], v[54:55], off
	s_nop 0
	global_load_dwordx2 v[66:67], v[66:67], off
	s_nop 0
	global_load_dwordx2 v[68:69], v[68:69], off
	s_nop 0
	global_load_dwordx2 v[40:41], v[40:41], off
	s_nop 0
	global_load_dwordx2 v[52:53], v[52:53], off
	s_nop 0
	global_load_dwordx2 v[58:59], v[58:59], off
	s_nop 0
	global_load_dwordx2 v[70:71], v[70:71], off
	s_nop 0
	global_load_dwordx2 v[72:73], v[72:73], off
	s_nop 0
	global_load_dwordx2 v[60:61], v[60:61], off
	s_nop 0
	global_load_dwordx2 v[56:57], v[56:57], off
	s_add_i32 s17, s17, s19
	v_add_co_u32_e32 v26, vcc, s24, v18
	v_mov_b64_e32 v[22:23], s[18:19]
	s_nop 0
	v_addc_co_u32_e32 v27, vcc, 0, v19, vcc
	s_add_i32 s25, s25, s92
	s_add_i32 s20, s20, s21
	s_cmpk_lt_i32 s25, 0x800
	s_waitcnt vmcnt(19)
	v_lshlrev_b32_e32 v33, 16, v31
	v_lshlrev_b32_e32 v32, 16, v30
	v_and_b32_e32 v79, 0xffff0000, v31
	v_and_b32_e32 v78, 0xffff0000, v30
	v_pk_add_f32 v[28:29], v[32:33], v[78:79]
	s_waitcnt vmcnt(18)
	v_cvt_f32_f16_e32 v80, v44
	v_add_f32_e32 v10, v28, v29
	v_cvt_f32_f16_sdwa v81, v44 dst_sel:DWORD dst_unused:UNUSED_PAD src0_sel:WORD_1
	s_waitcnt vmcnt(17)
	v_cvt_f32_f16_e32 v82, v46
	v_add_f32_dpp v10, v10, v10 quad_perm:[1,0,3,2] row_mask:0xf bank_mask:0xf bound_ctrl:1
	v_cvt_f32_f16_sdwa v83, v46 dst_sel:DWORD dst_unused:UNUSED_PAD src0_sel:WORD_1
	s_waitcnt vmcnt(16)
	v_lshlrev_b32_e32 v28, 16, v42
	v_add_f32_dpp v10, v10, v10 quad_perm:[2,3,0,1] row_mask:0xf bank_mask:0xf bound_ctrl:1
	v_and_b32_e32 v29, 0xffff0000, v42
	s_waitcnt vmcnt(15)
	v_cvt_f32_f16_e32 v84, v62
	v_cvt_f32_f16_sdwa v85, v62 dst_sel:DWORD dst_unused:UNUSED_PAD src0_sel:WORD_1
	v_lshlrev_b32_e32 v30, 16, v43
	v_and_b32_e32 v31, 0xffff0000, v43
	v_cvt_f32_f16_e32 v42, v63
	v_cvt_f32_f16_sdwa v43, v63 dst_sel:DWORD dst_unused:UNUSED_PAD src0_sel:WORD_1
	s_waitcnt vmcnt(14)
; __device__ __forceinline__ void phase3c(const Params& p) {
;     ...
; #pragma unroll
;         for (int u = 0; u < U; ++u) {
;             const int t = NMETA + (c4 * U + u) * 32 + (tid >> 4);
;             y[u][0] = __uint_as_float(yb2[u].x << 16); y[u][1] = __uint_as_float(yb2[u].x & 0xffff0000u); y[u][2] = __uint_as_float(yb2[u].y << 16); y[u][3] = __uint_as_float(yb2[u].y & 0xffff0000u);
;             const float mean = reduce16((y[u][0] + y[u][1]) + (y[u][2] + y[u][3])) * (1.0f / 64.0f);
;             const f32x4 dy = y[u] - mean;
;             const float var = reduce16((dy[0] * dy[0] + dy[1] * dy[1]) + (dy[2] * dy[2] + dy[3] * dy[3])) * (1.0f / 64.0f);
;             const float rs = rsqrtf(var + GN_EPS);
;             float bs = 0.f;
; #pragma unroll
;             for (int j = 0; j < 4; ++j) bs += (float)r4[u][j] * (float)k4[u][j] * rk[j];
;             bs = reduce16(bs);
	v_lshlrev_b32_e32 v63, 16, v51
	v_lshlrev_b32_e32 v62, 16, v50
	v_and_b32_e32 v51, 0xffff0000, v51
	v_and_b32_e32 v50, 0xffff0000, v50
	v_cvt_f32_f16_e32 v44, v45
	v_cvt_f32_f16_sdwa v45, v45 dst_sel:DWORD dst_unused:UNUSED_PAD src0_sel:WORD_1
	v_cvt_f32_f16_e32 v46, v47
	v_cvt_f32_f16_sdwa v47, v47 dst_sel:DWORD dst_unused:UNUSED_PAD src0_sel:WORD_1
	v_add_f32_dpp v10, v10, v10 row_half_mirror row_mask:0xf bank_mask:0xf bound_ctrl:1
	v_pk_add_f32 v[88:89], v[62:63], v[50:51]
	s_waitcnt vmcnt(12)
	v_cvt_f32_f16_e32 v90, v74
	v_cvt_f32_f16_sdwa v91, v74 dst_sel:DWORD dst_unused:UNUSED_PAD src0_sel:WORD_1
	s_waitcnt vmcnt(11)
	v_cvt_f32_f16_e32 v92, v64
	v_cvt_f32_f16_sdwa v93, v64 dst_sel:DWORD dst_unused:UNUSED_PAD src0_sel:WORD_1
	v_cvt_f32_f16_e32 v74, v75
	v_cvt_f32_f16_sdwa v75, v75 dst_sel:DWORD dst_unused:UNUSED_PAD src0_sel:WORD_1
	v_cvt_f32_f16_e32 v64, v65
	v_cvt_f32_f16_sdwa v65, v65 dst_sel:DWORD dst_unused:UNUSED_PAD src0_sel:WORD_1
	s_waitcnt vmcnt(9)
	v_lshlrev_b32_e32 v97, 16, v55
	v_lshlrev_b32_e32 v96, 16, v54
	v_and_b32_e32 v55, 0xffff0000, v55
	v_and_b32_e32 v54, 0xffff0000, v54
	s_waitcnt vmcnt(8)
	v_cvt_f32_f16_e32 v98, v66
	v_cvt_f32_f16_sdwa v99, v66 dst_sel:DWORD dst_unused:UNUSED_PAD src0_sel:WORD_1
	s_waitcnt vmcnt(7)
	v_cvt_f32_f16_e32 v100, v68
	v_cvt_f32_f16_sdwa v101, v68 dst_sel:DWORD dst_unused:UNUSED_PAD src0_sel:WORD_1
	s_waitcnt vmcnt(4)
	v_lshlrev_b32_e32 v107, 16, v59
	v_lshlrev_b32_e32 v106, 16, v58
	v_and_b32_e32 v59, 0xffff0000, v59
	v_and_b32_e32 v58, 0xffff0000, v58
	v_cvt_f32_f16_e32 v66, v67
	v_cvt_f32_f16_sdwa v67, v67 dst_sel:DWORD dst_unused:UNUSED_PAD src0_sel:WORD_1
	v_cvt_f32_f16_e32 v68, v69
	v_cvt_f32_f16_sdwa v69, v69 dst_sel:DWORD dst_unused:UNUSED_PAD src0_sel:WORD_1
	s_waitcnt vmcnt(3)
	v_cvt_f32_f16_e32 v108, v70
	v_cvt_f32_f16_sdwa v109, v70 dst_sel:DWORD dst_unused:UNUSED_PAD src0_sel:WORD_1
	s_waitcnt vmcnt(2)
	v_cvt_f32_f16_e32 v110, v72
	v_cvt_f32_f16_sdwa v111, v72 dst_sel:DWORD dst_unused:UNUSED_PAD src0_sel:WORD_1
	v_cvt_f32_f16_e32 v70, v71
	v_cvt_f32_f16_sdwa v71, v71 dst_sel:DWORD dst_unused:UNUSED_PAD src0_sel:WORD_1
	v_cvt_f32_f16_e32 v72, v73
	v_cvt_f32_f16_sdwa v73, v73 dst_sel:DWORD dst_unused:UNUSED_PAD src0_sel:WORD_1
	v_add_f32_dpp v10, v10, v10 row_mirror row_mask:0xf bank_mask:0xf bound_ctrl:1
	v_add_f32_e32 v118, v88, v89
	v_pk_add_f32 v[88:89], v[96:97], v[54:55]
	v_pk_add_f32 v[116:117], v[106:107], v[58:59]
	v_fmac_f32_e32 v78, 0xbc800000, v10
	v_fmac_f32_e32 v32, 0xbc800000, v10
	v_fmac_f32_e32 v79, 0xbc800000, v10
	v_fmac_f32_e32 v33, 0xbc800000, v10
	v_add_f32_dpp v10, v118, v118 quad_perm:[1,0,3,2] row_mask:0xf bank_mask:0xf bound_ctrl:1
	v_add_f32_e32 v118, v88, v89
	v_add_f32_e32 v116, v116, v117
	v_mov_b32_e32 v88, v33
	v_mov_b32_e32 v89, v79
	v_mov_b32_e32 v33, v78
	v_pk_mul_f32 v[78:79], v[80:81], v[82:83]
	v_add_f32_dpp v10, v10, v10 quad_perm:[2,3,0,1] row_mask:0xf bank_mask:0xf bound_ctrl:1
	v_add_f32_dpp v117, v118, v118 quad_perm:[1,0,3,2] row_mask:0xf bank_mask:0xf bound_ctrl:1
	v_add_f32_dpp v116, v116, v116 quad_perm:[1,0,3,2] row_mask:0xf bank_mask:0xf bound_ctrl:1
	v_pk_mul_f32 v[44:45], v[44:45], v[46:47]
	v_pk_mul_f32 v[46:47], v[88:89], v[88:89]
	v_pk_mul_f32 v[80:81], v[32:33], v[32:33]
	v_pk_mul_f32 v[78:79], v[36:37], v[78:79]
	v_add_f32_dpp v10, v10, v10 row_half_mirror row_mask:0xf bank_mask:0xf bound_ctrl:1
	v_pk_mul_f32 v[82:83], v[90:91], v[92:93]
	v_pk_mul_f32 v[64:65], v[74:75], v[64:65]
	v_add_f32_dpp v90, v117, v117 quad_perm:[2,3,0,1] row_mask:0xf bank_mask:0xf bound_ctrl:1
	v_pk_mul_f32 v[74:75], v[98:99], v[100:101]
	v_add_f32_dpp v91, v116, v116 quad_perm:[2,3,0,1] row_mask:0xf bank_mask:0xf bound_ctrl:1
	v_pk_mul_f32 v[66:67], v[66:67], v[68:69]
	v_pk_mul_f32 v[68:69], v[108:109], v[110:111]
	v_pk_mul_f32 v[70:71], v[70:71], v[72:73]
	v_pk_mov_b32 v[72:73], v[80:81], v[46:47] op_sel:[1,0]
	v_mov_b32_e32 v81, v47
	v_add_f32_e32 v78, 0, v78
	v_add_f32_dpp v10, v10, v10 row_mirror row_mask:0xf bank_mask:0xf bound_ctrl:1
	v_pk_mul_f32 v[46:47], v[36:37], v[82:83]
	v_add_f32_dpp v82, v90, v90 row_half_mirror row_mask:0xf bank_mask:0xf bound_ctrl:1
	v_pk_mul_f32 v[74:75], v[36:37], v[74:75]
	v_add_f32_dpp v83, v91, v91 row_half_mirror row_mask:0xf bank_mask:0xf bound_ctrl:1
	v_pk_mul_f32 v[44:45], v[38:39], v[44:45]
	v_pk_mul_f32 v[64:65], v[38:39], v[64:65]
	v_pk_mul_f32 v[66:67], v[38:39], v[66:67]
	v_pk_mul_f32 v[36:37], v[36:37], v[68:69]
	v_pk_mul_f32 v[38:39], v[38:39], v[70:71]
	v_pk_add_f32 v[68:69], v[72:73], v[80:81]
	v_add_f32_e32 v70, v79, v78
	v_fmac_f32_e32 v50, 0xbc800000, v10
	v_fmac_f32_e32 v62, 0xbc800000, v10
	v_fmac_f32_e32 v51, 0xbc800000, v10
	v_fmac_f32_e32 v63, 0xbc800000, v10
	v_add_f32_e32 v10, 0, v46
	v_add_f32_dpp v46, v82, v82 row_mirror row_mask:0xf bank_mask:0xf bound_ctrl:1
	v_add_f32_e32 v72, 0, v74
	v_add_f32_dpp v73, v83, v83 row_mirror row_mask:0xf bank_mask:0xf bound_ctrl:1
	v_add_f32_e32 v36, 0, v36
	v_add_f32_e32 v44, v44, v70
	v_mov_b32_e32 v70, v63
	v_mov_b32_e32 v71, v51
	v_mov_b32_e32 v63, v50
	v_add_f32_e32 v10, v47, v10
	v_fmac_f32_e32 v54, 0xbc800000, v46
	v_fmac_f32_e32 v55, 0xbc800000, v46
	v_fmac_f32_e32 v97, 0xbc800000, v46
	v_add_f32_e32 v50, v75, v72
	v_fmac_f32_e32 v58, 0xbc800000, v73
	v_fmac_f32_e32 v59, 0xbc800000, v73
	v_fmac_f32_e32 v107, 0xbc800000, v73
	v_mov_b32_e32 v51, v68
	v_fmac_f32_e32 v96, 0xbc800000, v46
	v_fmac_f32_e32 v106, 0xbc800000, v73
	v_add_f32_e32 v68, v37, v36
	v_add_f32_e32 v72, v45, v44
	v_pk_mul_f32 v[36:37], v[70:71], v[70:71]
	v_pk_mul_f32 v[44:45], v[62:63], v[62:63]
	v_add_f32_e32 v10, v64, v10
	v_mov_b32_e32 v46, v97
	v_mov_b32_e32 v47, v55
; __device__ __forceinline__ void phase3c(const Params& p) {
;     ...
;             const float mean = reduce16((y[u][0] + y[u][1]) + (y[u][2] + y[u][3])) * (1.0f / 64.0f);
;             const f32x4 dy = y[u] - mean;
;             const float var = reduce16((dy[0] * dy[0] + dy[1] * dy[1]) + (dy[2] * dy[2] + dy[3] * dy[3])) * (1.0f / 64.0f);
;             const float rs = rsqrtf(var + GN_EPS);
;             float bs = 0.f;
; #pragma unroll
;             for (int j = 0; j < 4; ++j) bs += (float)r4[u][j] * (float)k4[u][j] * rk[j];
;             bs = reduce16(bs);
	v_mov_b32_e32 v97, v54
	v_add_f32_e32 v50, v66, v50
	v_mov_b32_e32 v54, v107
	v_mov_b32_e32 v55, v59
	v_mov_b32_e32 v107, v58
	v_add_f32_e32 v38, v38, v68
	v_add_f32_dpp v68, v72, v72 quad_perm:[1,0,3,2] row_mask:0xf bank_mask:0xf bound_ctrl:1
	v_pk_mov_b32 v[58:59], v[44:45], v[36:37] op_sel:[1,0]
	v_mov_b32_e32 v45, v37
	v_add_f32_e32 v10, v65, v10
	v_pk_mul_f32 v[36:37], v[46:47], v[46:47]
	v_pk_mul_f32 v[64:65], v[96:97], v[96:97]
	v_add_f32_e32 v50, v67, v50
	v_pk_mul_f32 v[66:67], v[54:55], v[54:55]
	v_pk_mul_f32 v[72:73], v[106:107], v[106:107]
	v_add_f32_e32 v74, v39, v38
	v_add_f32_dpp v68, v68, v68 quad_perm:[2,3,0,1] row_mask:0xf bank_mask:0xf bound_ctrl:1
	v_pk_add_f32 v[38:39], v[58:59], v[44:45]
	v_pk_mov_b32 v[44:45], v[64:65], v[36:37] op_sel:[1,0]
	v_mov_b32_e32 v65, v37
	v_pk_mov_b32 v[36:37], v[72:73], v[66:67] op_sel:[1,0]
	v_mov_b32_e32 v73, v67
	v_add_f32_dpp v58, v50, v50 quad_perm:[1,0,3,2] row_mask:0xf bank_mask:0xf bound_ctrl:1
	v_add_f32_dpp v66, v68, v68 row_half_mirror row_mask:0xf bank_mask:0xf bound_ctrl:1
	v_mov_b32_e32 v50, v38
	v_mov_b32_e32 v68, v39
	v_pk_add_f32 v[38:39], v[44:45], v[64:65]
	v_pk_add_f32 v[36:37], v[36:37], v[72:73]
	v_pk_add_f32 v[44:45], v[50:51], v[68:69]
	v_mov_b32_e32 v50, v36
	v_mov_b32_e32 v51, v38
	v_mov_b32_e32 v38, v37
	v_add_f32_dpp v10, v10, v10 quad_perm:[1,0,3,2] row_mask:0xf bank_mask:0xf bound_ctrl:1
	v_mov_b32_dpp v37, v45 quad_perm:[1,0,3,2] row_mask:0xf bank_mask:0xf bound_ctrl:1
	v_mov_b32_dpp v36, v44 quad_perm:[1,0,3,2] row_mask:0xf bank_mask:0xf bound_ctrl:1
	v_pk_add_f32 v[38:39], v[50:51], v[38:39]
	v_add_f32_dpp v67, v10, v10 quad_perm:[2,3,0,1] row_mask:0xf bank_mask:0xf bound_ctrl:1
	v_pk_add_f32 v[36:37], v[44:45], v[36:37]
	v_mov_b32_dpp v45, v39 quad_perm:[1,0,3,2] row_mask:0xf bank_mask:0xf bound_ctrl:1
	v_mov_b32_dpp v44, v38 quad_perm:[1,0,3,2] row_mask:0xf bank_mask:0xf bound_ctrl:1
	v_add_f32_dpp v10, v66, v66 row_mirror row_mask:0xf bank_mask:0xf bound_ctrl:1
	v_add_f32_dpp v64, v67, v67 row_half_mirror row_mask:0xf bank_mask:0xf bound_ctrl:1
	v_mov_b32_dpp v67, v37 quad_perm:[2,3,0,1] row_mask:0xf bank_mask:0xf bound_ctrl:1
	v_mov_b32_dpp v66, v36 quad_perm:[2,3,0,1] row_mask:0xf bank_mask:0xf bound_ctrl:1
	v_pk_add_f32 v[38:39], v[38:39], v[44:45]
	v_pk_add_f32 v[36:37], v[36:37], v[66:67]
	v_add_f32_dpp v59, v74, v74 quad_perm:[1,0,3,2] row_mask:0xf bank_mask:0xf bound_ctrl:1
	v_mov_b32_dpp v45, v39 quad_perm:[2,3,0,1] row_mask:0xf bank_mask:0xf bound_ctrl:1
	v_mov_b32_dpp v44, v38 quad_perm:[2,3,0,1] row_mask:0xf bank_mask:0xf bound_ctrl:1
	v_mov_b32_dpp v67, v37 row_half_mirror row_mask:0xf bank_mask:0xf bound_ctrl:1
	v_mov_b32_dpp v66, v36 row_half_mirror row_mask:0xf bank_mask:0xf bound_ctrl:1
	v_pk_add_f32 v[38:39], v[38:39], v[44:45]
	v_pk_add_f32 v[36:37], v[36:37], v[66:67]
	v_cvt_f32_f16_e32 v86, v48
	v_mov_b32_dpp v45, v39 row_half_mirror row_mask:0xf bank_mask:0xf bound_ctrl:1
	v_mov_b32_dpp v44, v38 row_half_mirror row_mask:0xf bank_mask:0xf bound_ctrl:1
	v_mov_b32_dpp v67, v37 row_mirror row_mask:0xf bank_mask:0xf bound_ctrl:1
	v_mov_b32_dpp v66, v36 row_mirror row_mask:0xf bank_mask:0xf bound_ctrl:1
	v_pk_add_f32 v[38:39], v[38:39], v[44:45]
	v_pk_add_f32 v[36:37], v[36:37], v[66:67]
	v_cvt_f32_f16_sdwa v87, v48 dst_sel:DWORD dst_unused:UNUSED_PAD src0_sel:WORD_1
	v_mov_b32_dpp v45, v39 row_mirror row_mask:0xf bank_mask:0xf bound_ctrl:1
	v_mov_b32_dpp v44, v38 row_mirror row_mask:0xf bank_mask:0xf bound_ctrl:1
	v_pk_fma_f32 v[36:37], v[36:37], s[16:17], v[16:17] op_sel_hi:[1,0,0]
	v_pk_add_f32 v[38:39], v[38:39], v[44:45]
	v_mul_f32_e32 v44, 0x4b800000, v37
	v_mul_f32_e32 v45, 0x4b800000, v36
	v_cmp_gt_f32_e32 vcc, s23, v36
	v_pk_fma_f32 v[22:23], v[38:39], s[16:17], v[22:23] op_sel_hi:[1,0,0]
	v_cmp_gt_f32_e64 s[0:1], s23, v37
	v_cndmask_b32_e32 v36, v36, v45, vcc
	v_mul_f32_e32 v38, 0x4b800000, v23
	v_cndmask_b32_e64 v37, v37, v44, s[0:1]
	v_cmp_gt_f32_e64 s[6:7], s23, v23
	v_mul_f32_e32 v39, 0x4b800000, v22
	v_cmp_gt_f32_e64 s[4:5], s23, v22
	v_rsq_f32_e32 v37, v37
	v_rsq_f32_e32 v36, v36
	v_cndmask_b32_e64 v23, v23, v38, s[6:7]
	v_cndmask_b32_e64 v22, v22, v39, s[4:5]
	v_rsq_f32_e32 v44, v23
	v_rsq_f32_e32 v45, v22
	v_cvt_f32_f16_e32 v48, v49
	v_cvt_f32_f16_sdwa v49, v49 dst_sel:DWORD dst_unused:UNUSED_PAD src0_sel:WORD_1
	v_add_f32_dpp v59, v59, v59 quad_perm:[2,3,0,1] row_mask:0xf bank_mask:0xf bound_ctrl:1
	v_mul_f32_e32 v22, 0x45800000, v37
	v_mul_f32_e32 v23, 0x45800000, v36
	v_cvt_f32_f16_e32 v104, v52
	v_cvt_f32_f16_sdwa v105, v52 dst_sel:DWORD dst_unused:UNUSED_PAD src0_sel:WORD_1
	v_cvt_f32_f16_e32 v52, v53
	v_cvt_f32_f16_sdwa v53, v53 dst_sel:DWORD dst_unused:UNUSED_PAD src0_sel:WORD_1
	v_add_f32_dpp v59, v59, v59 row_half_mirror row_mask:0xf bank_mask:0xf bound_ctrl:1
	v_cndmask_b32_e64 v22, v37, v22, s[0:1]
	v_cndmask_b32_e32 v36, v36, v23, vcc
	v_mul_f32_e32 v51, 0x45800000, v44
	s_waitcnt vmcnt(0)
; __device__ __forceinline__ unsigned pk_bf16(float lo, float hi) { const f32x2 v = {lo, hi}; return __builtin_bit_cast(unsigned, __builtin_convertvector(v, b16x2)); }
; __device__ __forceinline__ void phase3c(const Params& p) {
;     ...
;             const float rs = rsqrtf(var + GN_EPS);
;             float bs = 0.f;
; #pragma unroll
;             for (int j = 0; j < 4; ++j) bs += (float)r4[u][j] * (float)k4[u][j] * rk[j];
;             bs = reduce16(bs);
;             const float gg[4] = {__uint_as_float(g2[u].x << 16), __uint_as_float(g2[u].x & 0xffff0000u), __uint_as_float(g2[u].y << 16), __uint_as_float(g2[u].y & 0xffff0000u)};
;             float o[4];
; #pragma unroll
;             for (int j = 0; j < 4; ++j) o[j] = (dy[j] * rs * gain[j] + bias[j] + bs * (float)v4[u][j]) * gg[j];
;             u32x2 w; w.x = pk_bf16(o[0], o[1]); w.y = pk_bf16(o[2], o[3]);
;             *(u32x2*)(orw + (size_t)(b * SEQ + t - NMETA) * 512 + c) = w;
;         }
	v_cvt_f32_f16_e32 v114, v56
	v_cvt_f32_f16_sdwa v115, v56 dst_sel:DWORD dst_unused:UNUSED_PAD src0_sel:WORD_1
	v_cvt_f32_f16_e32 v56, v57
	v_cvt_f32_f16_sdwa v57, v57 dst_sel:DWORD dst_unused:UNUSED_PAD src0_sel:WORD_1
	v_add_f32_dpp v58, v58, v58 quad_perm:[2,3,0,1] row_mask:0xf bank_mask:0xf bound_ctrl:1
	v_add_f32_dpp v50, v59, v59 row_mirror row_mask:0xf bank_mask:0xf bound_ctrl:1
	v_mul_f32_e32 v59, 0x45800000, v45
	v_pk_mul_f32 v[32:33], v[32:33], v[22:23] op_sel_hi:[1,0]
	v_pk_mul_f32 v[22:23], v[88:89], v[22:23] op_sel_hi:[1,0]
	v_pk_mul_f32 v[38:39], v[62:63], v[36:37] op_sel_hi:[1,0]
	v_pk_mul_f32 v[36:37], v[70:71], v[36:37] op_sel_hi:[1,0]
	v_cndmask_b32_e64 v44, v44, v51, s[6:7]
	v_add_f32_dpp v65, v58, v58 row_half_mirror row_mask:0xf bank_mask:0xf bound_ctrl:1
	v_add_f32_dpp v58, v64, v64 row_mirror row_mask:0xf bank_mask:0xf bound_ctrl:1
	v_cndmask_b32_e64 v62, v45, v59, s[4:5]
	v_pk_fma_f32 v[32:33], v[0:1], v[32:33], v[4:5]
	v_pk_fma_f32 v[22:23], v[2:3], v[22:23], v[6:7]
	v_pk_fma_f32 v[38:39], v[0:1], v[38:39], v[4:5]
	v_pk_fma_f32 v[36:37], v[2:3], v[36:37], v[6:7]
	v_pk_mul_f32 v[66:67], v[96:97], v[44:45] op_sel_hi:[1,0]
	v_pk_mul_f32 v[44:45], v[46:47], v[44:45] op_sel_hi:[1,0]
	v_lshlrev_b32_e32 v94, 16, v76
	v_and_b32_e32 v95, 0xffff0000, v76
	v_lshlrev_b32_e32 v76, 16, v77
	v_and_b32_e32 v77, 0xffff0000, v77
	v_add_f32_dpp v64, v65, v65 row_mirror row_mask:0xf bank_mask:0xf bound_ctrl:1
	v_pk_mul_f32 v[46:47], v[106:107], v[62:63] op_sel_hi:[1,0]
	v_pk_mul_f32 v[54:55], v[54:55], v[62:63] op_sel_hi:[1,0]
	v_pk_fma_f32 v[32:33], v[10:11], v[84:85], v[32:33] op_sel_hi:[0,1,1]
	v_pk_fma_f32 v[22:23], v[10:11], v[42:43], v[22:23] op_sel_hi:[0,1,1]
	v_pk_fma_f32 v[38:39], v[58:59], v[86:87], v[38:39] op_sel_hi:[0,1,1]
	v_pk_fma_f32 v[36:37], v[58:59], v[48:49], v[36:37] op_sel_hi:[0,1,1]
	v_pk_fma_f32 v[42:43], v[0:1], v[66:67], v[4:5]
	v_pk_fma_f32 v[44:45], v[2:3], v[44:45], v[6:7]
	v_lshlrev_b32_e32 v102, 16, v40
	v_and_b32_e32 v103, 0xffff0000, v40
	v_lshlrev_b32_e32 v40, 16, v41
	v_and_b32_e32 v41, 0xffff0000, v41
	v_pk_fma_f32 v[0:1], v[0:1], v[46:47], v[4:5]
	v_pk_fma_f32 v[2:3], v[2:3], v[54:55], v[6:7]
	v_pk_mul_f32 v[4:5], v[32:33], v[28:29]
	v_pk_mul_f32 v[6:7], v[22:23], v[30:31]
	v_pk_mul_f32 v[22:23], v[38:39], v[94:95]
	v_pk_mul_f32 v[28:29], v[36:37], v[76:77]
	v_pk_fma_f32 v[30:31], v[64:65], v[104:105], v[42:43] op_sel_hi:[0,1,1]
	v_pk_fma_f32 v[32:33], v[64:65], v[52:53], v[44:45] op_sel_hi:[0,1,1]
	v_lshlrev_b32_e32 v112, 16, v60
	v_and_b32_e32 v113, 0xffff0000, v60
	v_lshlrev_b32_e32 v60, 16, v61
	v_and_b32_e32 v61, 0xffff0000, v61
	v_pk_fma_f32 v[0:1], v[50:51], v[114:115], v[0:1] op_sel_hi:[0,1,1]
	v_pk_fma_f32 v[2:3], v[50:51], v[56:57], v[2:3] op_sel_hi:[0,1,1]
	v_cvt_pk_bf16_f32 v4, v4, v5
	v_cvt_pk_bf16_f32 v5, v6, v7
	v_cvt_pk_bf16_f32 v6, v22, v23
	v_cvt_pk_bf16_f32 v7, v28, v29
	v_pk_mul_f32 v[22:23], v[30:31], v[102:103]
	v_pk_mul_f32 v[28:29], v[32:33], v[40:41]
	v_pk_mul_f32 v[0:1], v[0:1], v[112:113]
	v_pk_mul_f32 v[2:3], v[2:3], v[60:61]
	global_store_dwordx2 v[18:19], v[4:5], off sc1
	global_store_dwordx2 v[26:27], v[6:7], off sc1
	v_cvt_pk_bf16_f32 v4, v22, v23
	v_cvt_pk_bf16_f32 v5, v28, v29
	v_cvt_pk_bf16_f32 v0, v0, v1
	v_cvt_pk_bf16_f32 v1, v2, v3
	global_store_dwordx2 v[20:21], v[4:5], off sc1
	global_store_dwordx2 v[24:25], v[0:1], off sc1
	s_cbranch_scc1 .LBB0_953

; __device__ __forceinline__ unsigned pk_bf16(float lo, float hi) { const f32x2 v = {lo, hi}; return __builtin_bit_cast(unsigned, __builtin_convertvector(v, b16x2)); }
;     __device__ __forceinline__ void row(int r, int col32, int fq, const f32x4& a00, const f32x4& a01, const f32x4& a10, const f32x4& a11) const { half(r, col32, fq, a00, a01); half(r, col32 + HALF, fq, a10, a11); }
;     __device__ __forceinline__ void row(int r, int col32, int fq, const f32x4& a00, const f32x4& a01, const f32x4& a10, const f32x4& a11) const { half(r, col32, fq, a00, a01); half(r, col32 + HALF, fq, a10, a11); }
;     ...
;             const int brow = cur.pm * BM, bcol = cur.pn * BM;
; #pragma unroll
;             for (int ai = 0; ai < 2; ++ai)
; #pragma unroll
;                 for (int m = 0; m < 4; ++m) {
;                     E.row(brow + ai * HALF + wr * 64 + m * 16 + fr, bcol + wc * 32, fq, acc[ai][0][m][0], acc[ai][0][m][1], acc[ai][1][m][0], acc[ai][1][m][1]);
;                     asm volatile("" ::: "memory");
;                 }
;     __device__ __forceinline__ void half(int row, int col32, int fq, const f32x4& v0, const f32x4& v1) const {
;         const int col = col32 + 8 * fq;
;         float g[8], a[8]; bf8_to_f(*(const u32x4*)(gates + (size_t)row * 2048 + 1024 + col), g); bf8_to_f(*(const u32x4*)(t1 + (size_t)row * D + col), a);
;         u32x4 w; w.x = pk_bf16(a[0] + v0[0] * g[0], a[1] + v0[1] * g[1]); w.y = pk_bf16(a[2] + v0[2] * g[2], a[3] + v0[3] * g[3]);
;         w.z = pk_bf16(a[4] + v1[0] * g[4], a[5] + v1[1] * g[5]); w.w = pk_bf16(a[6] + v1[2] * g[6], a[7] + v1[3] * g[7]);
;         *(u32x4*)(m + (size_t)row * D + col) = w;
;     }
;     __device__ __forceinline__ void row(int r, int col32, int fq, const f32x4& a00, const f32x4& a01, const f32x4& a10, const f32x4& a11) const { half(r, col32, fq, a00, a01); half(r, col32 + HALF, fq, a10, a11); }
.LBB0_1050:
	v_lshl_add_u32 v154, s26, 8, v129
	v_lshl_or_b32 v152, s46, 8, v135
	v_ashrrev_i32_e32 v155, 31, v154
	v_ashrrev_i32_e32 v153, 31, v152
	v_lshlrev_b64 v[176:177], 12, v[154:155]
	v_lshlrev_b64 v[184:185], 11, v[154:155]
	v_lshl_add_u64 v[176:177], s[88:89], 0, v[176:177]
	v_lshlrev_b64 v[152:153], 1, v[152:153]
	v_add_u32_e32 v236, 0x0, v154
	v_ashrrev_i32_e32 v237, 31, v236
	v_lshlrev_b64 v[238:239], 12, v[236:237]
	v_lshlrev_b64 v[240:241], 11, v[236:237]
	v_lshl_add_u64 v[238:239], s[88:89], 0, v[238:239]
	v_lshl_add_u64 v[240:241], s[8:9], 0, v[240:241]
	v_lshl_add_u64 v[238:239], v[238:239], 0, v[152:153]
	v_lshl_add_u64 v[240:241], v[240:241], 0, v[152:153]
	global_load_dwordx4 v[200:203], v[238:239], off offset:2048
	global_load_dwordx4 v[204:207], v[240:241], off
	global_load_dwordx4 v[208:211], v[240:241], off offset:256
	global_load_dwordx4 v[212:215], v[238:239], off offset:2304
	s_nop 0
	v_add_u32_e32 v236, 0x10, v154
	v_ashrrev_i32_e32 v237, 31, v236
	v_lshlrev_b64 v[238:239], 12, v[236:237]
	v_lshlrev_b64 v[240:241], 11, v[236:237]
	v_lshl_add_u64 v[238:239], s[88:89], 0, v[238:239]
	v_lshl_add_u64 v[240:241], s[8:9], 0, v[240:241]
	v_lshl_add_u64 v[238:239], v[238:239], 0, v[152:153]
	v_lshl_add_u64 v[240:241], v[240:241], 0, v[152:153]
	global_load_dwordx4 v[216:219], v[238:239], off offset:2048
	global_load_dwordx4 v[220:223], v[240:241], off
	global_load_dwordx4 v[228:231], v[240:241], off offset:256
	global_load_dwordx4 v[232:235], v[238:239], off offset:2304
	s_nop 0
	v_lshl_add_u64 v[180:181], s[8:9], 0, v[184:185]
	v_lshl_add_u64 v[188:189], v[176:177], 0, v[152:153]
	v_lshl_add_u64 v[186:187], v[180:181], 0, v[152:153]
	v_lshl_add_u64 v[184:185], s[10:11], 0, v[184:185]
	v_lshl_add_u64 v[190:191], v[184:185], 0, v[152:153]
	s_andn2_b64 vcc, exec, s[6:7]
	s_mov_b64 s[6:7], -1
	s_waitcnt vmcnt(7)
	v_lshlrev_b32_e32 v192, 16, v200
	v_and_b32_e32 v193, 0xffff0000, v200
	s_waitcnt vmcnt(6)
	v_lshlrev_b32_e32 v194, 16, v204
	v_and_b32_e32 v195, 0xffff0000, v204
	v_lshlrev_b32_e32 v176, 16, v201
	v_and_b32_e32 v177, 0xffff0000, v201
	v_lshlrev_b32_e32 v180, 16, v205
	v_and_b32_e32 v181, 0xffff0000, v205
	v_lshlrev_b32_e32 v196, 16, v202
	v_and_b32_e32 v197, 0xffff0000, v202
	v_lshlrev_b32_e32 v198, 16, v206
	v_and_b32_e32 v199, 0xffff0000, v206
	v_lshlrev_b32_e32 v178, 16, v203
	v_and_b32_e32 v179, 0xffff0000, v203
	v_lshlrev_b32_e32 v182, 16, v207
	v_and_b32_e32 v183, 0xffff0000, v207
	v_pk_fma_f32 v[124:125], v[124:125], v[192:193], v[194:195]
	v_pk_fma_f32 v[126:127], v[126:127], v[176:177], v[180:181]
	v_pk_fma_f32 v[176:177], v[120:121], v[196:197], v[198:199]
	v_pk_fma_f32 v[178:179], v[122:123], v[178:179], v[182:183]
	v_cvt_pk_bf16_f32 v120, v124, v125
	v_cvt_pk_bf16_f32 v121, v126, v127
	v_cvt_pk_bf16_f32 v122, v176, v177
	v_cvt_pk_bf16_f32 v123, v178, v179
	global_store_dwordx4 v[190:191], v[120:123], off sc1
	v_or_b32_e32 v124, 16, v154
	s_waitcnt vmcnt(6)
	v_lshlrev_b32_e32 v178, 16, v208
	v_and_b32_e32 v179, 0xffff0000, v208
	v_lshlrev_b32_e32 v180, 16, v209
	v_and_b32_e32 v181, 0xffff0000, v209
	v_lshlrev_b32_e32 v182, 16, v210
	v_and_b32_e32 v183, 0xffff0000, v210
	v_lshlrev_b32_e32 v184, 16, v211
	v_and_b32_e32 v185, 0xffff0000, v211
	v_ashrrev_i32_e32 v125, 31, v124
	v_lshlrev_b64 v[126:127], 12, v[124:125]
	v_lshlrev_b64 v[124:125], 11, v[124:125]
	v_lshl_add_u64 v[126:127], s[88:89], 0, v[126:127]
	v_lshl_add_u64 v[176:177], s[8:9], 0, v[124:125]
	v_lshl_add_u64 v[126:127], v[126:127], 0, v[152:153]
	s_waitcnt vmcnt(5)
	v_lshlrev_b32_e32 v186, 16, v212
	v_and_b32_e32 v187, 0xffff0000, v212
	v_lshlrev_b32_e32 v120, 16, v213
	v_and_b32_e32 v121, 0xffff0000, v213
	v_lshlrev_b32_e32 v188, 16, v214
	v_and_b32_e32 v189, 0xffff0000, v214
	v_lshlrev_b32_e32 v122, 16, v215
	v_and_b32_e32 v123, 0xffff0000, v215
	v_add_u32_e32 v236, 0x20, v154
	v_ashrrev_i32_e32 v237, 31, v236
	v_lshlrev_b64 v[238:239], 12, v[236:237]
	v_lshlrev_b64 v[240:241], 11, v[236:237]
	v_lshl_add_u64 v[238:239], s[88:89], 0, v[238:239]
	v_lshl_add_u64 v[240:241], s[8:9], 0, v[240:241]
	v_lshl_add_u64 v[238:239], v[238:239], 0, v[152:153]
	v_lshl_add_u64 v[240:241], v[240:241], 0, v[152:153]
	global_load_dwordx4 v[200:203], v[238:239], off offset:2048
	global_load_dwordx4 v[204:207], v[240:241], off
	global_load_dwordx4 v[208:211], v[240:241], off offset:256
	global_load_dwordx4 v[212:215], v[238:239], off offset:2304
	s_nop 0
	v_pk_fma_f32 v[116:117], v[116:117], v[186:187], v[178:179]
	v_pk_fma_f32 v[118:119], v[118:119], v[120:121], v[180:181]
	v_pk_fma_f32 v[120:121], v[112:113], v[188:189], v[182:183]
	v_pk_fma_f32 v[122:123], v[114:115], v[122:123], v[184:185]
	v_cvt_pk_bf16_f32 v112, v116, v117
	v_cvt_pk_bf16_f32 v113, v118, v119
	v_cvt_pk_bf16_f32 v114, v120, v121
	v_cvt_pk_bf16_f32 v115, v122, v123
	global_store_dwordx4 v[190:191], v[112:115], off offset:256 sc1
	v_lshl_add_u64 v[120:121], v[176:177], 0, v[152:153]
	v_lshl_add_u64 v[122:123], s[10:11], 0, v[124:125]
	v_lshl_add_u64 v[124:125], v[122:123], 0, v[152:153]
	s_waitcnt vmcnt(9)
	v_lshlrev_b32_e32 v176, 16, v216
	v_and_b32_e32 v177, 0xffff0000, v216
	s_waitcnt vmcnt(8)
; __device__ __forceinline__ unsigned pk_bf16(float lo, float hi) { const f32x2 v = {lo, hi}; return __builtin_bit_cast(unsigned, __builtin_convertvector(v, b16x2)); }
;     __device__ __forceinline__ void row(int r, int col32, int fq, const f32x4& a00, const f32x4& a01, const f32x4& a10, const f32x4& a11) const { half(r, col32, fq, a00, a01); half(r, col32 + HALF, fq, a10, a11); }
;     __device__ __forceinline__ void row(int r, int col32, int fq, const f32x4& a00, const f32x4& a01, const f32x4& a10, const f32x4& a11) const { half(r, col32, fq, a00, a01); half(r, col32 + HALF, fq, a10, a11); }
;     ...
;             const int brow = cur.pm * BM, bcol = cur.pn * BM;
; #pragma unroll
;             for (int ai = 0; ai < 2; ++ai)
; #pragma unroll
;                 for (int m = 0; m < 4; ++m) {
;                     E.row(brow + ai * HALF + wr * 64 + m * 16 + fr, bcol + wc * 32, fq, acc[ai][0][m][0], acc[ai][0][m][1], acc[ai][1][m][0], acc[ai][1][m][1]);
;                     asm volatile("" ::: "memory");
;                 }
;     __device__ __forceinline__ void half(int row, int col32, int fq, const f32x4& v0, const f32x4& v1) const {
;         const int col = col32 + 8 * fq;
;         float g[8], a[8]; bf8_to_f(*(const u32x4*)(gates + (size_t)row * 2048 + 1024 + col), g); bf8_to_f(*(const u32x4*)(t1 + (size_t)row * D + col), a);
;         u32x4 w; w.x = pk_bf16(a[0] + v0[0] * g[0], a[1] + v0[1] * g[1]); w.y = pk_bf16(a[2] + v0[2] * g[2], a[3] + v0[3] * g[3]);
;         w.z = pk_bf16(a[4] + v1[0] * g[4], a[5] + v1[1] * g[5]); w.w = pk_bf16(a[6] + v1[2] * g[6], a[7] + v1[3] * g[7]);
;         *(u32x4*)(m + (size_t)row * D + col) = w;
;     }
;     __device__ __forceinline__ void row(int r, int col32, int fq, const f32x4& a00, const f32x4& a01, const f32x4& a10, const f32x4& a11) const { half(r, col32, fq, a00, a01); half(r, col32 + HALF, fq, a10, a11); }
	v_lshlrev_b32_e32 v178, 16, v220
	v_and_b32_e32 v179, 0xffff0000, v220
	v_lshlrev_b32_e32 v112, 16, v217
	v_and_b32_e32 v113, 0xffff0000, v217
	v_lshlrev_b32_e32 v116, 16, v221
	v_and_b32_e32 v117, 0xffff0000, v221
	v_lshlrev_b32_e32 v180, 16, v218
	v_and_b32_e32 v181, 0xffff0000, v218
	v_lshlrev_b32_e32 v182, 16, v222
	v_and_b32_e32 v183, 0xffff0000, v222
	v_lshlrev_b32_e32 v114, 16, v219
	v_and_b32_e32 v115, 0xffff0000, v219
	v_lshlrev_b32_e32 v118, 16, v223
	v_and_b32_e32 v119, 0xffff0000, v223
	v_pk_fma_f32 v[108:109], v[108:109], v[176:177], v[178:179]
	v_pk_fma_f32 v[110:111], v[110:111], v[112:113], v[116:117]
	v_pk_fma_f32 v[112:113], v[104:105], v[180:181], v[182:183]
	v_pk_fma_f32 v[114:115], v[106:107], v[114:115], v[118:119]
	v_cvt_pk_bf16_f32 v104, v108, v109
	v_cvt_pk_bf16_f32 v105, v110, v111
	v_cvt_pk_bf16_f32 v106, v112, v113
	v_cvt_pk_bf16_f32 v107, v114, v115
	global_store_dwordx4 v[124:125], v[104:107], off sc1
	v_or_b32_e32 v108, 32, v154
	s_waitcnt vmcnt(8)
	v_lshlrev_b32_e32 v114, 16, v228
	v_and_b32_e32 v115, 0xffff0000, v228
	v_lshlrev_b32_e32 v116, 16, v229
	v_and_b32_e32 v117, 0xffff0000, v229
	v_lshlrev_b32_e32 v118, 16, v230
	v_and_b32_e32 v119, 0xffff0000, v230
	v_lshlrev_b32_e32 v120, 16, v231
	v_and_b32_e32 v121, 0xffff0000, v231
	v_ashrrev_i32_e32 v109, 31, v108
	v_lshlrev_b64 v[110:111], 12, v[108:109]
	v_lshlrev_b64 v[108:109], 11, v[108:109]
	v_lshl_add_u64 v[110:111], s[88:89], 0, v[110:111]
	v_lshl_add_u64 v[112:113], s[8:9], 0, v[108:109]
	v_lshl_add_u64 v[110:111], v[110:111], 0, v[152:153]
	s_waitcnt vmcnt(7)
	v_lshlrev_b32_e32 v122, 16, v232
	v_and_b32_e32 v123, 0xffff0000, v232
	v_lshlrev_b32_e32 v104, 16, v233
	v_and_b32_e32 v105, 0xffff0000, v233
	v_lshlrev_b32_e32 v126, 16, v234
	v_and_b32_e32 v127, 0xffff0000, v234
	v_lshlrev_b32_e32 v106, 16, v235
	v_and_b32_e32 v107, 0xffff0000, v235
	v_add_u32_e32 v236, 0x30, v154
	v_ashrrev_i32_e32 v237, 31, v236
	v_lshlrev_b64 v[238:239], 12, v[236:237]
	v_lshlrev_b64 v[240:241], 11, v[236:237]
	v_lshl_add_u64 v[238:239], s[88:89], 0, v[238:239]
	v_lshl_add_u64 v[240:241], s[8:9], 0, v[240:241]
	v_lshl_add_u64 v[238:239], v[238:239], 0, v[152:153]
	v_lshl_add_u64 v[240:241], v[240:241], 0, v[152:153]
	global_load_dwordx4 v[216:219], v[238:239], off offset:2048
	global_load_dwordx4 v[220:223], v[240:241], off
	global_load_dwordx4 v[228:231], v[240:241], off offset:256
	global_load_dwordx4 v[232:235], v[238:239], off offset:2304
	s_nop 0
	v_pk_fma_f32 v[100:101], v[100:101], v[122:123], v[114:115]
	v_pk_fma_f32 v[102:103], v[102:103], v[104:105], v[116:117]
	v_pk_fma_f32 v[104:105], v[96:97], v[126:127], v[118:119]
	v_pk_fma_f32 v[106:107], v[98:99], v[106:107], v[120:121]
	v_cvt_pk_bf16_f32 v96, v100, v101
	v_cvt_pk_bf16_f32 v97, v102, v103
	v_cvt_pk_bf16_f32 v98, v104, v105
	v_cvt_pk_bf16_f32 v99, v106, v107
	global_store_dwordx4 v[124:125], v[96:99], off offset:256 sc1
	v_lshl_add_u64 v[104:105], v[112:113], 0, v[152:153]
	v_lshl_add_u64 v[106:107], s[10:11], 0, v[108:109]
	v_lshl_add_u64 v[108:109], v[106:107], 0, v[152:153]
	s_waitcnt vmcnt(10)
	v_lshlrev_b32_e32 v112, 16, v200
	v_and_b32_e32 v113, 0xffff0000, v200
	s_waitcnt vmcnt(9)
	v_lshlrev_b32_e32 v114, 16, v204
	v_and_b32_e32 v115, 0xffff0000, v204
	v_lshlrev_b32_e32 v96, 16, v201
	v_and_b32_e32 v97, 0xffff0000, v201
	v_lshlrev_b32_e32 v100, 16, v205
	v_and_b32_e32 v101, 0xffff0000, v205
	v_lshlrev_b32_e32 v116, 16, v202
	v_and_b32_e32 v117, 0xffff0000, v202
	v_lshlrev_b32_e32 v118, 16, v206
	v_and_b32_e32 v119, 0xffff0000, v206
	v_lshlrev_b32_e32 v98, 16, v203
	v_and_b32_e32 v99, 0xffff0000, v203
	v_lshlrev_b32_e32 v102, 16, v207
	v_and_b32_e32 v103, 0xffff0000, v207
	v_pk_fma_f32 v[92:93], v[92:93], v[112:113], v[114:115]
	v_pk_fma_f32 v[94:95], v[94:95], v[96:97], v[100:101]
	v_pk_fma_f32 v[96:97], v[88:89], v[116:117], v[118:119]
	v_pk_fma_f32 v[98:99], v[90:91], v[98:99], v[102:103]
	v_cvt_pk_bf16_f32 v88, v92, v93
	v_cvt_pk_bf16_f32 v89, v94, v95
	v_cvt_pk_bf16_f32 v90, v96, v97
	v_cvt_pk_bf16_f32 v91, v98, v99
	global_store_dwordx4 v[108:109], v[88:91], off sc1
	v_or_b32_e32 v92, 48, v154
	s_waitcnt vmcnt(9)
	v_lshlrev_b32_e32 v98, 16, v208
	v_and_b32_e32 v99, 0xffff0000, v208
	v_lshlrev_b32_e32 v100, 16, v209
	v_and_b32_e32 v101, 0xffff0000, v209
	v_lshlrev_b32_e32 v102, 16, v210
	v_and_b32_e32 v103, 0xffff0000, v210
	v_lshlrev_b32_e32 v104, 16, v211
	v_and_b32_e32 v105, 0xffff0000, v211
	v_ashrrev_i32_e32 v93, 31, v92
	v_lshlrev_b64 v[94:95], 12, v[92:93]
	v_lshlrev_b64 v[92:93], 11, v[92:93]
	v_lshl_add_u64 v[94:95], s[88:89], 0, v[94:95]
	v_lshl_add_u64 v[96:97], s[8:9], 0, v[92:93]
	v_lshl_add_u64 v[94:95], v[94:95], 0, v[152:153]
	s_waitcnt vmcnt(8)
	v_lshlrev_b32_e32 v106, 16, v212
	v_and_b32_e32 v107, 0xffff0000, v212
	v_lshlrev_b32_e32 v88, 16, v213
	v_and_b32_e32 v89, 0xffff0000, v213
	v_lshlrev_b32_e32 v110, 16, v214
	v_and_b32_e32 v111, 0xffff0000, v214
	v_lshlrev_b32_e32 v90, 16, v215
	v_and_b32_e32 v91, 0xffff0000, v215
	v_add_u32_e32 v236, 0x80, v154
	v_ashrrev_i32_e32 v237, 31, v236
	v_lshlrev_b64 v[238:239], 12, v[236:237]
	v_lshlrev_b64 v[240:241], 11, v[236:237]
	v_lshl_add_u64 v[238:239], s[88:89], 0, v[238:239]
	v_lshl_add_u64 v[240:241], s[8:9], 0, v[240:241]
	v_lshl_add_u64 v[238:239], v[238:239], 0, v[152:153]
	v_lshl_add_u64 v[240:241], v[240:241], 0, v[152:153]
	global_load_dwordx4 v[200:203], v[238:239], off offset:2048
	global_load_dwordx4 v[204:207], v[240:241], off
	global_load_dwordx4 v[208:211], v[240:241], off offset:256
	global_load_dwordx4 v[212:215], v[238:239], off offset:2304
	s_nop 0
	v_pk_fma_f32 v[84:85], v[84:85], v[106:107], v[98:99]
	v_pk_fma_f32 v[86:87], v[86:87], v[88:89], v[100:101]
	v_pk_fma_f32 v[88:89], v[80:81], v[110:111], v[102:103]
	v_pk_fma_f32 v[90:91], v[82:83], v[90:91], v[104:105]
	v_cvt_pk_bf16_f32 v80, v84, v85
	v_cvt_pk_bf16_f32 v81, v86, v87
	v_cvt_pk_bf16_f32 v82, v88, v89
	v_cvt_pk_bf16_f32 v83, v90, v91
	global_store_dwordx4 v[108:109], v[80:83], off offset:256 sc1
	v_lshl_add_u64 v[88:89], v[96:97], 0, v[152:153]
	v_lshl_add_u64 v[90:91], s[10:11], 0, v[92:93]
	v_lshl_add_u64 v[92:93], v[90:91], 0, v[152:153]
	s_waitcnt vmcnt(10)
; __device__ __forceinline__ unsigned pk_bf16(float lo, float hi) { const f32x2 v = {lo, hi}; return __builtin_bit_cast(unsigned, __builtin_convertvector(v, b16x2)); }
;     __device__ __forceinline__ void row(int r, int col32, int fq, const f32x4& a00, const f32x4& a01, const f32x4& a10, const f32x4& a11) const { half(r, col32, fq, a00, a01); half(r, col32 + HALF, fq, a10, a11); }
;     __device__ __forceinline__ void row(int r, int col32, int fq, const f32x4& a00, const f32x4& a01, const f32x4& a10, const f32x4& a11) const { half(r, col32, fq, a00, a01); half(r, col32 + HALF, fq, a10, a11); }
;     ...
;             const int brow = cur.pm * BM, bcol = cur.pn * BM;
; #pragma unroll
;             for (int ai = 0; ai < 2; ++ai)
; #pragma unroll
;                 for (int m = 0; m < 4; ++m) {
;                     E.row(brow + ai * HALF + wr * 64 + m * 16 + fr, bcol + wc * 32, fq, acc[ai][0][m][0], acc[ai][0][m][1], acc[ai][1][m][0], acc[ai][1][m][1]);
;                     asm volatile("" ::: "memory");
;                 }
;     __device__ __forceinline__ void half(int row, int col32, int fq, const f32x4& v0, const f32x4& v1) const {
;         const int col = col32 + 8 * fq;
;         float g[8], a[8]; bf8_to_f(*(const u32x4*)(gates + (size_t)row * 2048 + 1024 + col), g); bf8_to_f(*(const u32x4*)(t1 + (size_t)row * D + col), a);
;         u32x4 w; w.x = pk_bf16(a[0] + v0[0] * g[0], a[1] + v0[1] * g[1]); w.y = pk_bf16(a[2] + v0[2] * g[2], a[3] + v0[3] * g[3]);
;         w.z = pk_bf16(a[4] + v1[0] * g[4], a[5] + v1[1] * g[5]); w.w = pk_bf16(a[6] + v1[2] * g[6], a[7] + v1[3] * g[7]);
;         *(u32x4*)(m + (size_t)row * D + col) = w;
;     }
;     __device__ __forceinline__ void row(int r, int col32, int fq, const f32x4& a00, const f32x4& a01, const f32x4& a10, const f32x4& a11) const { half(r, col32, fq, a00, a01); half(r, col32 + HALF, fq, a10, a11); }
	v_lshlrev_b32_e32 v96, 16, v216
	v_and_b32_e32 v97, 0xffff0000, v216
	s_waitcnt vmcnt(9)
	v_lshlrev_b32_e32 v98, 16, v220
	v_and_b32_e32 v99, 0xffff0000, v220
	v_lshlrev_b32_e32 v80, 16, v217
	v_and_b32_e32 v81, 0xffff0000, v217
	v_lshlrev_b32_e32 v84, 16, v221
	v_and_b32_e32 v85, 0xffff0000, v221
	v_lshlrev_b32_e32 v100, 16, v218
	v_and_b32_e32 v101, 0xffff0000, v218
	v_lshlrev_b32_e32 v102, 16, v222
	v_and_b32_e32 v103, 0xffff0000, v222
	v_lshlrev_b32_e32 v82, 16, v219
	v_and_b32_e32 v83, 0xffff0000, v219
	v_lshlrev_b32_e32 v86, 16, v223
	v_and_b32_e32 v87, 0xffff0000, v223
	v_pk_fma_f32 v[76:77], v[76:77], v[96:97], v[98:99]
	v_pk_fma_f32 v[78:79], v[78:79], v[80:81], v[84:85]
	v_pk_fma_f32 v[80:81], v[72:73], v[100:101], v[102:103]
	v_pk_fma_f32 v[82:83], v[74:75], v[82:83], v[86:87]
	v_cvt_pk_bf16_f32 v72, v76, v77
	v_cvt_pk_bf16_f32 v73, v78, v79
	v_cvt_pk_bf16_f32 v74, v80, v81
	v_cvt_pk_bf16_f32 v75, v82, v83
	global_store_dwordx4 v[92:93], v[72:75], off sc1
	v_add_u32_e32 v76, 0x80, v154
	s_waitcnt vmcnt(9)
	v_lshlrev_b32_e32 v82, 16, v228
	v_and_b32_e32 v83, 0xffff0000, v228
	v_lshlrev_b32_e32 v84, 16, v229
	v_and_b32_e32 v85, 0xffff0000, v229
	v_lshlrev_b32_e32 v86, 16, v230
	v_and_b32_e32 v87, 0xffff0000, v230
	v_lshlrev_b32_e32 v88, 16, v231
	v_and_b32_e32 v89, 0xffff0000, v231
	v_ashrrev_i32_e32 v77, 31, v76
	v_lshlrev_b64 v[78:79], 12, v[76:77]
	v_lshlrev_b64 v[76:77], 11, v[76:77]
	v_lshl_add_u64 v[78:79], s[88:89], 0, v[78:79]
	v_lshl_add_u64 v[80:81], s[8:9], 0, v[76:77]
	v_lshl_add_u64 v[78:79], v[78:79], 0, v[152:153]
	s_waitcnt vmcnt(8)
	v_lshlrev_b32_e32 v90, 16, v232
	v_and_b32_e32 v91, 0xffff0000, v232
	v_lshlrev_b32_e32 v72, 16, v233
	v_and_b32_e32 v73, 0xffff0000, v233
	v_lshlrev_b32_e32 v94, 16, v234
	v_and_b32_e32 v95, 0xffff0000, v234
	v_lshlrev_b32_e32 v74, 16, v235
	v_and_b32_e32 v75, 0xffff0000, v235
	v_add_u32_e32 v236, 0x90, v154
	v_ashrrev_i32_e32 v237, 31, v236
	v_lshlrev_b64 v[238:239], 12, v[236:237]
	v_lshlrev_b64 v[240:241], 11, v[236:237]
	v_lshl_add_u64 v[238:239], s[88:89], 0, v[238:239]
	v_lshl_add_u64 v[240:241], s[8:9], 0, v[240:241]
	v_lshl_add_u64 v[238:239], v[238:239], 0, v[152:153]
	v_lshl_add_u64 v[240:241], v[240:241], 0, v[152:153]
	global_load_dwordx4 v[216:219], v[238:239], off offset:2048
	global_load_dwordx4 v[220:223], v[240:241], off
	global_load_dwordx4 v[228:231], v[240:241], off offset:256
	global_load_dwordx4 v[232:235], v[238:239], off offset:2304
	s_nop 0
	v_pk_fma_f32 v[68:69], v[68:69], v[90:91], v[82:83]
	v_pk_fma_f32 v[70:71], v[70:71], v[72:73], v[84:85]
	v_pk_fma_f32 v[72:73], v[64:65], v[94:95], v[86:87]
	v_pk_fma_f32 v[74:75], v[66:67], v[74:75], v[88:89]
	v_cvt_pk_bf16_f32 v64, v68, v69
	v_cvt_pk_bf16_f32 v65, v70, v71
	v_cvt_pk_bf16_f32 v66, v72, v73
	v_cvt_pk_bf16_f32 v67, v74, v75
	global_store_dwordx4 v[92:93], v[64:67], off offset:256 sc1
	v_lshl_add_u64 v[72:73], v[80:81], 0, v[152:153]
	v_lshl_add_u64 v[74:75], s[10:11], 0, v[76:77]
	v_lshl_add_u64 v[76:77], v[74:75], 0, v[152:153]
	s_waitcnt vmcnt(10)
	v_lshlrev_b32_e32 v80, 16, v200
	v_and_b32_e32 v81, 0xffff0000, v200
	s_waitcnt vmcnt(9)
	v_lshlrev_b32_e32 v82, 16, v204
	v_and_b32_e32 v83, 0xffff0000, v204
	v_lshlrev_b32_e32 v64, 16, v201
	v_and_b32_e32 v65, 0xffff0000, v201
	v_lshlrev_b32_e32 v68, 16, v205
	v_and_b32_e32 v69, 0xffff0000, v205
	v_lshlrev_b32_e32 v84, 16, v202
	v_and_b32_e32 v85, 0xffff0000, v202
	v_lshlrev_b32_e32 v86, 16, v206
	v_and_b32_e32 v87, 0xffff0000, v206
	v_lshlrev_b32_e32 v66, 16, v203
	v_and_b32_e32 v67, 0xffff0000, v203
	v_lshlrev_b32_e32 v70, 16, v207
	v_and_b32_e32 v71, 0xffff0000, v207
	v_pk_fma_f32 v[60:61], v[60:61], v[80:81], v[82:83]
	v_pk_fma_f32 v[62:63], v[62:63], v[64:65], v[68:69]
	v_pk_fma_f32 v[64:65], v[56:57], v[84:85], v[86:87]
	v_pk_fma_f32 v[66:67], v[58:59], v[66:67], v[70:71]
	v_cvt_pk_bf16_f32 v56, v60, v61
	v_cvt_pk_bf16_f32 v57, v62, v63
	v_cvt_pk_bf16_f32 v58, v64, v65
	v_cvt_pk_bf16_f32 v59, v66, v67
	global_store_dwordx4 v[76:77], v[56:59], off sc1
	v_add_u32_e32 v60, 0x90, v154
	s_waitcnt vmcnt(9)
	v_lshlrev_b32_e32 v66, 16, v208
	v_and_b32_e32 v67, 0xffff0000, v208
	v_lshlrev_b32_e32 v68, 16, v209
	v_and_b32_e32 v69, 0xffff0000, v209
	v_lshlrev_b32_e32 v70, 16, v210
	v_and_b32_e32 v71, 0xffff0000, v210
	v_lshlrev_b32_e32 v72, 16, v211
	v_and_b32_e32 v73, 0xffff0000, v211
	v_ashrrev_i32_e32 v61, 31, v60
	v_lshlrev_b64 v[62:63], 12, v[60:61]
	v_lshlrev_b64 v[60:61], 11, v[60:61]
	v_lshl_add_u64 v[62:63], s[88:89], 0, v[62:63]
	v_lshl_add_u64 v[64:65], s[8:9], 0, v[60:61]
	v_lshl_add_u64 v[62:63], v[62:63], 0, v[152:153]
	s_waitcnt vmcnt(8)
	v_lshlrev_b32_e32 v74, 16, v212
	v_and_b32_e32 v75, 0xffff0000, v212
	v_lshlrev_b32_e32 v56, 16, v213
	v_and_b32_e32 v57, 0xffff0000, v213
	v_lshlrev_b32_e32 v78, 16, v214
	v_and_b32_e32 v79, 0xffff0000, v214
	v_lshlrev_b32_e32 v58, 16, v215
	v_and_b32_e32 v59, 0xffff0000, v215
	v_add_u32_e32 v236, 0xa0, v154
	v_ashrrev_i32_e32 v237, 31, v236
	v_lshlrev_b64 v[238:239], 12, v[236:237]
	v_lshlrev_b64 v[240:241], 11, v[236:237]
	v_lshl_add_u64 v[238:239], s[88:89], 0, v[238:239]
	v_lshl_add_u64 v[240:241], s[8:9], 0, v[240:241]
	v_lshl_add_u64 v[238:239], v[238:239], 0, v[152:153]
	v_lshl_add_u64 v[240:241], v[240:241], 0, v[152:153]
	global_load_dwordx4 v[200:203], v[238:239], off offset:2048
	global_load_dwordx4 v[204:207], v[240:241], off
	global_load_dwordx4 v[208:211], v[240:241], off offset:256
	global_load_dwordx4 v[212:215], v[238:239], off offset:2304
	s_nop 0
	v_pk_fma_f32 v[52:53], v[52:53], v[74:75], v[66:67]
	v_pk_fma_f32 v[54:55], v[54:55], v[56:57], v[68:69]
	v_pk_fma_f32 v[56:57], v[48:49], v[78:79], v[70:71]
	v_pk_fma_f32 v[58:59], v[50:51], v[58:59], v[72:73]
	v_cvt_pk_bf16_f32 v48, v52, v53
	v_cvt_pk_bf16_f32 v49, v54, v55
	v_cvt_pk_bf16_f32 v50, v56, v57
	v_cvt_pk_bf16_f32 v51, v58, v59
	global_store_dwordx4 v[76:77], v[48:51], off offset:256 sc1
	v_lshl_add_u64 v[56:57], v[64:65], 0, v[152:153]
	v_lshl_add_u64 v[58:59], s[10:11], 0, v[60:61]
	v_lshl_add_u64 v[60:61], v[58:59], 0, v[152:153]
	s_waitcnt vmcnt(10)
; __device__ __forceinline__ unsigned pk_bf16(float lo, float hi) { const f32x2 v = {lo, hi}; return __builtin_bit_cast(unsigned, __builtin_convertvector(v, b16x2)); }
;     __device__ __forceinline__ void row(int r, int col32, int fq, const f32x4& a00, const f32x4& a01, const f32x4& a10, const f32x4& a11) const { half(r, col32, fq, a00, a01); half(r, col32 + HALF, fq, a10, a11); }
;     __device__ __forceinline__ void row(int r, int col32, int fq, const f32x4& a00, const f32x4& a01, const f32x4& a10, const f32x4& a11) const { half(r, col32, fq, a00, a01); half(r, col32 + HALF, fq, a10, a11); }
;     ...
;             const int brow = cur.pm * BM, bcol = cur.pn * BM;
; #pragma unroll
;             for (int ai = 0; ai < 2; ++ai)
; #pragma unroll
;                 for (int m = 0; m < 4; ++m) {
;                     E.row(brow + ai * HALF + wr * 64 + m * 16 + fr, bcol + wc * 32, fq, acc[ai][0][m][0], acc[ai][0][m][1], acc[ai][1][m][0], acc[ai][1][m][1]);
;                     asm volatile("" ::: "memory");
;                 }
;     __device__ __forceinline__ void half(int row, int col32, int fq, const f32x4& v0, const f32x4& v1) const {
;         const int col = col32 + 8 * fq;
;         float g[8], a[8]; bf8_to_f(*(const u32x4*)(gates + (size_t)row * 2048 + 1024 + col), g); bf8_to_f(*(const u32x4*)(t1 + (size_t)row * D + col), a);
;         u32x4 w; w.x = pk_bf16(a[0] + v0[0] * g[0], a[1] + v0[1] * g[1]); w.y = pk_bf16(a[2] + v0[2] * g[2], a[3] + v0[3] * g[3]);
;         w.z = pk_bf16(a[4] + v1[0] * g[4], a[5] + v1[1] * g[5]); w.w = pk_bf16(a[6] + v1[2] * g[6], a[7] + v1[3] * g[7]);
;         *(u32x4*)(m + (size_t)row * D + col) = w;
;     }
;     __device__ __forceinline__ void row(int r, int col32, int fq, const f32x4& a00, const f32x4& a01, const f32x4& a10, const f32x4& a11) const { half(r, col32, fq, a00, a01); half(r, col32 + HALF, fq, a10, a11); }
	v_lshlrev_b32_e32 v64, 16, v216
	v_and_b32_e32 v65, 0xffff0000, v216
	s_waitcnt vmcnt(9)
	v_lshlrev_b32_e32 v66, 16, v220
	v_and_b32_e32 v67, 0xffff0000, v220
	v_lshlrev_b32_e32 v48, 16, v217
	v_and_b32_e32 v49, 0xffff0000, v217
	v_lshlrev_b32_e32 v52, 16, v221
	v_and_b32_e32 v53, 0xffff0000, v221
	v_lshlrev_b32_e32 v68, 16, v218
	v_and_b32_e32 v69, 0xffff0000, v218
	v_lshlrev_b32_e32 v70, 16, v222
	v_and_b32_e32 v71, 0xffff0000, v222
	v_lshlrev_b32_e32 v50, 16, v219
	v_and_b32_e32 v51, 0xffff0000, v219
	v_lshlrev_b32_e32 v54, 16, v223
	v_and_b32_e32 v55, 0xffff0000, v223
	v_pk_fma_f32 v[44:45], v[44:45], v[64:65], v[66:67]
	v_pk_fma_f32 v[46:47], v[46:47], v[48:49], v[52:53]
	v_pk_fma_f32 v[48:49], v[40:41], v[68:69], v[70:71]
	v_pk_fma_f32 v[50:51], v[42:43], v[50:51], v[54:55]
	v_cvt_pk_bf16_f32 v40, v44, v45
	v_cvt_pk_bf16_f32 v41, v46, v47
	v_cvt_pk_bf16_f32 v42, v48, v49
	v_cvt_pk_bf16_f32 v43, v50, v51
	global_store_dwordx4 v[60:61], v[40:43], off sc1
	v_add_u32_e32 v44, 0xa0, v154
	s_waitcnt vmcnt(9)
	v_lshlrev_b32_e32 v50, 16, v228
	v_and_b32_e32 v51, 0xffff0000, v228
	v_lshlrev_b32_e32 v52, 16, v229
	v_and_b32_e32 v53, 0xffff0000, v229
	v_lshlrev_b32_e32 v54, 16, v230
	v_and_b32_e32 v55, 0xffff0000, v230
	v_lshlrev_b32_e32 v56, 16, v231
	v_and_b32_e32 v57, 0xffff0000, v231
	v_ashrrev_i32_e32 v45, 31, v44
	v_lshlrev_b64 v[46:47], 12, v[44:45]
	v_lshlrev_b64 v[44:45], 11, v[44:45]
	v_lshl_add_u64 v[46:47], s[88:89], 0, v[46:47]
	v_lshl_add_u64 v[48:49], s[8:9], 0, v[44:45]
	v_lshl_add_u64 v[46:47], v[46:47], 0, v[152:153]
	s_waitcnt vmcnt(8)
	v_lshlrev_b32_e32 v58, 16, v232
	v_and_b32_e32 v59, 0xffff0000, v232
	v_lshlrev_b32_e32 v40, 16, v233
	v_and_b32_e32 v41, 0xffff0000, v233
	v_lshlrev_b32_e32 v62, 16, v234
	v_and_b32_e32 v63, 0xffff0000, v234
	v_lshlrev_b32_e32 v42, 16, v235
	v_and_b32_e32 v43, 0xffff0000, v235
	v_add_u32_e32 v236, 0xb0, v154
	v_ashrrev_i32_e32 v237, 31, v236
	v_lshlrev_b64 v[238:239], 12, v[236:237]
	v_lshlrev_b64 v[240:241], 11, v[236:237]
	v_lshl_add_u64 v[238:239], s[88:89], 0, v[238:239]
	v_lshl_add_u64 v[240:241], s[8:9], 0, v[240:241]
	v_lshl_add_u64 v[238:239], v[238:239], 0, v[152:153]
	v_lshl_add_u64 v[240:241], v[240:241], 0, v[152:153]
	global_load_dwordx4 v[216:219], v[238:239], off offset:2048
	global_load_dwordx4 v[220:223], v[240:241], off
	global_load_dwordx4 v[228:231], v[240:241], off offset:256
	global_load_dwordx4 v[232:235], v[238:239], off offset:2304
	s_nop 0
	v_pk_fma_f32 v[36:37], v[36:37], v[58:59], v[50:51]
	v_pk_fma_f32 v[38:39], v[38:39], v[40:41], v[52:53]
	v_pk_fma_f32 v[40:41], v[32:33], v[62:63], v[54:55]
	v_pk_fma_f32 v[42:43], v[34:35], v[42:43], v[56:57]
	v_cvt_pk_bf16_f32 v32, v36, v37
	v_cvt_pk_bf16_f32 v33, v38, v39
	v_cvt_pk_bf16_f32 v34, v40, v41
	v_cvt_pk_bf16_f32 v35, v42, v43
	global_store_dwordx4 v[60:61], v[32:35], off offset:256 sc1
	v_lshl_add_u64 v[40:41], v[48:49], 0, v[152:153]
	v_lshl_add_u64 v[42:43], s[10:11], 0, v[44:45]
	v_lshl_add_u64 v[44:45], v[42:43], 0, v[152:153]
	s_waitcnt vmcnt(10)
	v_lshlrev_b32_e32 v48, 16, v200
	v_and_b32_e32 v49, 0xffff0000, v200
	s_waitcnt vmcnt(9)
	v_lshlrev_b32_e32 v50, 16, v204
	v_and_b32_e32 v51, 0xffff0000, v204
	v_lshlrev_b32_e32 v32, 16, v201
	v_and_b32_e32 v33, 0xffff0000, v201
	v_lshlrev_b32_e32 v36, 16, v205
	v_and_b32_e32 v37, 0xffff0000, v205
	v_lshlrev_b32_e32 v52, 16, v202
	v_and_b32_e32 v53, 0xffff0000, v202
	v_lshlrev_b32_e32 v54, 16, v206
	v_and_b32_e32 v55, 0xffff0000, v206
	v_lshlrev_b32_e32 v34, 16, v203
	v_and_b32_e32 v35, 0xffff0000, v203
	v_lshlrev_b32_e32 v38, 16, v207
	v_and_b32_e32 v39, 0xffff0000, v207
	v_pk_fma_f32 v[28:29], v[28:29], v[48:49], v[50:51]
	v_pk_fma_f32 v[30:31], v[30:31], v[32:33], v[36:37]
	v_pk_fma_f32 v[32:33], v[24:25], v[52:53], v[54:55]
	v_pk_fma_f32 v[34:35], v[26:27], v[34:35], v[38:39]
	v_cvt_pk_bf16_f32 v24, v28, v29
	v_cvt_pk_bf16_f32 v25, v30, v31
	v_cvt_pk_bf16_f32 v26, v32, v33
	v_cvt_pk_bf16_f32 v27, v34, v35
	global_store_dwordx4 v[44:45], v[24:27], off sc1
	v_add_u32_e32 v28, 0xb0, v154
	s_waitcnt vmcnt(9)
; __device__ __forceinline__ unsigned pk_bf16(float lo, float hi) { const f32x2 v = {lo, hi}; return __builtin_bit_cast(unsigned, __builtin_convertvector(v, b16x2)); }
; #define PG8_BAR __builtin_amdgcn_s_barrier()
;     __device__ __forceinline__ void row(int r, int col32, int fq, const f32x4& a00, const f32x4& a01, const f32x4& a10, const f32x4& a11) const { half(r, col32, fq, a00, a01); half(r, col32 + HALF, fq, a10, a11); }
;     __device__ __forceinline__ void row(int r, int col32, int fq, const f32x4& a00, const f32x4& a01, const f32x4& a10, const f32x4& a11) const { half(r, col32, fq, a00, a01); half(r, col32 + HALF, fq, a10, a11); }
;     ...
;             const int brow = cur.pm * BM, bcol = cur.pn * BM;
; #pragma unroll
;             for (int ai = 0; ai < 2; ++ai)
; #pragma unroll
;                 for (int m = 0; m < 4; ++m) {
;                     E.row(brow + ai * HALF + wr * 64 + m * 16 + fr, bcol + wc * 32, fq, acc[ai][0][m][0], acc[ai][0][m][1], acc[ai][1][m][0], acc[ai][1][m][1]);
;                     asm volatile("" ::: "memory");
;                 }
;         }
;         if (!has_next) break;
; #pragma unroll
;         for (int a = 0; a < 2; ++a)
; #pragma unroll
;             for (int b = 0; b < 2; ++b)
; #pragma unroll
;                 for (int m = 0; m < 4; ++m)
; #pragma unroll
;                     for (int n = 0; n < 2; ++n) acc[a][b][m][n] = (f32x4){0.f, 0.f, 0.f, 0.f};
;         cur = nxt; cA = nA; cB = nB; ++ui;
;         if (wr == 1) PG8_BAR;
;     __device__ __forceinline__ void half(int row, int col32, int fq, const f32x4& v0, const f32x4& v1) const {
;         const int col = col32 + 8 * fq;
;         float g[8], a[8]; bf8_to_f(*(const u32x4*)(gates + (size_t)row * 2048 + 1024 + col), g); bf8_to_f(*(const u32x4*)(t1 + (size_t)row * D + col), a);
;         u32x4 w; w.x = pk_bf16(a[0] + v0[0] * g[0], a[1] + v0[1] * g[1]); w.y = pk_bf16(a[2] + v0[2] * g[2], a[3] + v0[3] * g[3]);
;         w.z = pk_bf16(a[4] + v1[0] * g[4], a[5] + v1[1] * g[5]); w.w = pk_bf16(a[6] + v1[2] * g[6], a[7] + v1[3] * g[7]);
;         *(u32x4*)(m + (size_t)row * D + col) = w;
;     }
;     __device__ __forceinline__ void row(int r, int col32, int fq, const f32x4& a00, const f32x4& a01, const f32x4& a10, const f32x4& a11) const { half(r, col32, fq, a00, a01); half(r, col32 + HALF, fq, a10, a11); }
	v_lshlrev_b32_e32 v34, 16, v208
	v_and_b32_e32 v35, 0xffff0000, v208
	v_lshlrev_b32_e32 v36, 16, v209
	v_and_b32_e32 v37, 0xffff0000, v209
	v_lshlrev_b32_e32 v38, 16, v210
	v_and_b32_e32 v39, 0xffff0000, v210
	v_lshlrev_b32_e32 v40, 16, v211
	v_and_b32_e32 v41, 0xffff0000, v211
	v_ashrrev_i32_e32 v29, 31, v28
	v_lshlrev_b64 v[30:31], 12, v[28:29]
	v_lshlrev_b64 v[28:29], 11, v[28:29]
	v_lshl_add_u64 v[30:31], s[88:89], 0, v[30:31]
	v_lshl_add_u64 v[32:33], s[8:9], 0, v[28:29]
	v_lshl_add_u64 v[30:31], v[30:31], 0, v[152:153]
	s_waitcnt vmcnt(8)
	v_lshlrev_b32_e32 v42, 16, v212
	v_and_b32_e32 v43, 0xffff0000, v212
	v_lshlrev_b32_e32 v24, 16, v213
	v_and_b32_e32 v25, 0xffff0000, v213
	v_lshlrev_b32_e32 v46, 16, v214
	v_and_b32_e32 v47, 0xffff0000, v214
	v_lshlrev_b32_e32 v26, 16, v215
	v_and_b32_e32 v27, 0xffff0000, v215
	v_pk_fma_f32 v[20:21], v[20:21], v[42:43], v[34:35]
	v_pk_fma_f32 v[22:23], v[22:23], v[24:25], v[36:37]
	v_pk_fma_f32 v[24:25], v[16:17], v[46:47], v[38:39]
	v_pk_fma_f32 v[26:27], v[18:19], v[26:27], v[40:41]
	v_cvt_pk_bf16_f32 v16, v20, v21
	v_cvt_pk_bf16_f32 v17, v22, v23
	v_cvt_pk_bf16_f32 v18, v24, v25
	v_cvt_pk_bf16_f32 v19, v26, v27
	global_store_dwordx4 v[44:45], v[16:19], off offset:256 sc1
	v_lshl_add_u64 v[24:25], v[32:33], 0, v[152:153]
	v_lshl_add_u64 v[26:27], s[10:11], 0, v[28:29]
	v_lshl_add_u64 v[28:29], v[26:27], 0, v[152:153]
	s_waitcnt vmcnt(6)
	v_lshlrev_b32_e32 v32, 16, v216
	v_and_b32_e32 v33, 0xffff0000, v216
	s_waitcnt vmcnt(5)
	v_lshlrev_b32_e32 v34, 16, v220
	v_and_b32_e32 v35, 0xffff0000, v220
	v_lshlrev_b32_e32 v16, 16, v217
	v_and_b32_e32 v17, 0xffff0000, v217
	v_lshlrev_b32_e32 v20, 16, v221
	v_and_b32_e32 v21, 0xffff0000, v221
	v_lshlrev_b32_e32 v36, 16, v218
	v_and_b32_e32 v37, 0xffff0000, v218
	v_lshlrev_b32_e32 v38, 16, v222
	v_and_b32_e32 v39, 0xffff0000, v222
	v_lshlrev_b32_e32 v18, 16, v219
	v_and_b32_e32 v19, 0xffff0000, v219
	v_lshlrev_b32_e32 v22, 16, v223
	v_and_b32_e32 v23, 0xffff0000, v223
	v_pk_fma_f32 v[12:13], v[12:13], v[32:33], v[34:35]
	v_pk_fma_f32 v[14:15], v[14:15], v[16:17], v[20:21]
	v_pk_fma_f32 v[16:17], v[8:9], v[36:37], v[38:39]
	v_pk_fma_f32 v[18:19], v[10:11], v[18:19], v[22:23]
	v_cvt_pk_bf16_f32 v8, v12, v13
	v_cvt_pk_bf16_f32 v9, v14, v15
	v_cvt_pk_bf16_f32 v10, v16, v17
	v_cvt_pk_bf16_f32 v11, v18, v19
	global_store_dwordx4 v[28:29], v[8:11], off sc1
	s_waitcnt vmcnt(5)
	v_lshlrev_b32_e32 v12, 16, v228
	v_and_b32_e32 v13, 0xffff0000, v228
	v_lshlrev_b32_e32 v14, 16, v229
	v_and_b32_e32 v15, 0xffff0000, v229
	v_lshlrev_b32_e32 v16, 16, v230
	v_and_b32_e32 v17, 0xffff0000, v230
	v_lshlrev_b32_e32 v18, 16, v231
	v_and_b32_e32 v19, 0xffff0000, v231
	s_waitcnt vmcnt(4)
	v_lshlrev_b32_e32 v20, 16, v232
	v_and_b32_e32 v21, 0xffff0000, v232
	v_lshlrev_b32_e32 v8, 16, v233
	v_and_b32_e32 v9, 0xffff0000, v233
	v_lshlrev_b32_e32 v22, 16, v234
	v_and_b32_e32 v23, 0xffff0000, v234
	v_lshlrev_b32_e32 v10, 16, v235
	v_and_b32_e32 v11, 0xffff0000, v235
	v_pk_fma_f32 v[4:5], v[4:5], v[20:21], v[12:13]
	v_pk_fma_f32 v[6:7], v[6:7], v[8:9], v[14:15]
	v_pk_fma_f32 v[8:9], v[0:1], v[22:23], v[16:17]
	v_pk_fma_f32 v[10:11], v[2:3], v[10:11], v[18:19]
	v_cvt_pk_bf16_f32 v0, v4, v5
	v_cvt_pk_bf16_f32 v1, v6, v7
	v_cvt_pk_bf16_f32 v2, v8, v9
	v_cvt_pk_bf16_f32 v3, v10, v11
	global_store_dwordx4 v[28:29], v[0:3], off offset:256 sc1
	s_cbranch_vccnz .LBB0_1039
	s_andn2_b64 vcc, exec, s[0:1]
	s_cbranch_vccnz .LBB0_1038
	s_barrier
	s_branch .LBB0_1038

; __device__ __forceinline__ unsigned pk_bf16(float lo, float hi) { const f32x2 v = {lo, hi}; return __builtin_bit_cast(unsigned, __builtin_convertvector(v, b16x2)); }
;     __device__ __forceinline__ void row(int r, int col32, int fq, const f32x4& a00, const f32x4& a01, const f32x4& a10, const f32x4& a11) const { half(r, col32, fq, a00, a01); half(r, col32 + HALF, fq, a10, a11); }
;     __device__ __forceinline__ void row(int r, int col32, int fq, const f32x4& a00, const f32x4& a01, const f32x4& a10, const f32x4& a11) const { half(r, col32, fq, a00, a01); half(r, col32 + HALF, fq, a10, a11); }
;     __device__ __forceinline__ void row(int r, int col32, int fq, const f32x4& a00, const f32x4& a01, const f32x4& a10, const f32x4& a11) const { half(r, col32, fq, a00, a01); half(r, col32 + HALF, fq, a10, a11); }
;     ...
;             const int brow = cur.pm * BM, bcol = cur.pn * BM;
; #pragma unroll
;             for (int ai = 0; ai < 2; ++ai)
; #pragma unroll
;                 for (int m = 0; m < 4; ++m) {
;                     E.row(brow + ai * HALF + wr * 64 + m * 16 + fr, bcol + wc * 32, fq, acc[ai][0][m][0], acc[ai][0][m][1], acc[ai][1][m][0], acc[ai][1][m][1]);
;                     asm volatile("" ::: "memory");
;                 }
;     __device__ __forceinline__ void row(int r, int col32, int fq, const f32x4& a00, const f32x4& a01, const f32x4& a10, const f32x4& a11) const {
;         bf16_t* q = o + (size_t)r * D + col32 + 8 * fq;
;         u32x4 w0, w1;
;         w0.x = pk_bf16(a00[0], a00[1]); w0.y = pk_bf16(a00[2], a00[3]); w0.z = pk_bf16(a01[0], a01[1]); w0.w = pk_bf16(a01[2], a01[3]);
;         w1.x = pk_bf16(a10[0], a10[1]); w1.y = pk_bf16(a10[2], a10[3]); w1.z = pk_bf16(a11[0], a11[1]); w1.w = pk_bf16(a11[2], a11[3]);
;         *(u32x4*)q = w0; *(u32x4*)(q + HALF) = w1;
;     }
.LBB0_1126:
	s_lshl_b32 s21, s58, 8
	v_lshl_add_u32 v154, s18, 8, v150
	s_or_b32 s28, s21, s49
	s_ashr_i32 s29, s28, 31
	v_ashrrev_i32_e32 v155, 31, v154
	v_cvt_pk_bf16_f32 v108, v108, v109
	v_cvt_pk_bf16_f32 v109, v110, v111
	v_cvt_pk_bf16_f32 v110, v104, v105
	v_or_b32_e32 v104, 16, v154
	v_lshl_add_u64 v[172:173], s[28:29], 1, v[140:141]
	v_lshlrev_b64 v[174:175], 11, v[154:155]
	v_ashrrev_i32_e32 v105, 31, v104
	v_cvt_pk_bf16_f32 v92, v92, v93
	v_cvt_pk_bf16_f32 v93, v94, v95
	v_cvt_pk_bf16_f32 v94, v88, v89
	v_or_b32_e32 v88, 32, v154
	v_lshl_add_u64 v[174:175], v[172:173], 0, v[174:175]
	v_cvt_pk_bf16_f32 v124, v124, v125
	v_cvt_pk_bf16_f32 v125, v126, v127
	v_cvt_pk_bf16_f32 v126, v120, v121
	v_cvt_pk_bf16_f32 v127, v122, v123
	v_lshlrev_b64 v[104:105], 11, v[104:105]
	v_ashrrev_i32_e32 v89, 31, v88
	v_cvt_pk_bf16_f32 v76, v76, v77
	v_cvt_pk_bf16_f32 v77, v78, v79
	v_cvt_pk_bf16_f32 v78, v72, v73
	v_or_b32_e32 v72, 48, v154
	v_cvt_pk_bf16_f32 v111, v106, v107
	global_store_dwordx4 v[174:175], v[124:127], off sc1
	global_store_dwordx4 v[174:175], v[108:111], off offset:256 sc1
	v_cvt_pk_bf16_f32 v106, v112, v113
	v_cvt_pk_bf16_f32 v107, v114, v115
	v_lshl_add_u64 v[108:109], v[172:173], 0, v[104:105]
	v_cvt_pk_bf16_f32 v104, v116, v117
	v_cvt_pk_bf16_f32 v105, v118, v119
	v_lshlrev_b64 v[88:89], 11, v[88:89]
	v_ashrrev_i32_e32 v73, 31, v72
	v_cvt_pk_bf16_f32 v68, v68, v69
	v_cvt_pk_bf16_f32 v69, v70, v71
	v_cvt_pk_bf16_f32 v70, v64, v65
	v_add_u32_e32 v64, 0x80, v154
	v_cvt_pk_bf16_f32 v95, v90, v91
	global_store_dwordx4 v[108:109], v[104:107], off sc1
	global_store_dwordx4 v[108:109], v[92:95], off offset:256 sc1
	v_cvt_pk_bf16_f32 v90, v96, v97
	v_cvt_pk_bf16_f32 v91, v98, v99
	v_lshl_add_u64 v[92:93], v[172:173], 0, v[88:89]
	v_cvt_pk_bf16_f32 v88, v100, v101
	v_cvt_pk_bf16_f32 v89, v102, v103
	v_lshlrev_b64 v[72:73], 11, v[72:73]
	v_ashrrev_i32_e32 v65, 31, v64
	v_cvt_pk_bf16_f32 v44, v44, v45
	v_cvt_pk_bf16_f32 v45, v46, v47
	v_cvt_pk_bf16_f32 v46, v40, v41
	v_add_u32_e32 v40, 0x90, v154
	v_cvt_pk_bf16_f32 v79, v74, v75
	global_store_dwordx4 v[92:93], v[88:91], off sc1
	global_store_dwordx4 v[92:93], v[76:79], off offset:256 sc1
	v_cvt_pk_bf16_f32 v74, v80, v81
	v_cvt_pk_bf16_f32 v75, v82, v83
	v_lshl_add_u64 v[76:77], v[172:173], 0, v[72:73]
	v_cvt_pk_bf16_f32 v72, v84, v85
	v_cvt_pk_bf16_f32 v73, v86, v87
	v_lshlrev_b64 v[64:65], 11, v[64:65]
	v_ashrrev_i32_e32 v41, 31, v40
	v_cvt_pk_bf16_f32 v28, v28, v29
	v_cvt_pk_bf16_f32 v29, v30, v31
	v_cvt_pk_bf16_f32 v30, v24, v25
	v_add_u32_e32 v24, 0xa0, v154
	v_cvt_pk_bf16_f32 v71, v66, v67
	global_store_dwordx4 v[76:77], v[72:75], off sc1
	global_store_dwordx4 v[76:77], v[68:71], off offset:256 sc1
	v_lshl_add_u64 v[64:65], v[172:173], 0, v[64:65]
	v_cvt_pk_bf16_f32 v60, v60, v61
	v_cvt_pk_bf16_f32 v61, v62, v63
	v_cvt_pk_bf16_f32 v62, v56, v57
	v_cvt_pk_bf16_f32 v63, v58, v59
	v_lshlrev_b64 v[40:41], 11, v[40:41]
	v_ashrrev_i32_e32 v25, 31, v24
	v_cvt_pk_bf16_f32 v12, v12, v13
	v_cvt_pk_bf16_f32 v13, v14, v15
	v_cvt_pk_bf16_f32 v14, v8, v9
	v_add_u32_e32 v8, 0xb0, v154
	v_cvt_pk_bf16_f32 v47, v42, v43
	global_store_dwordx4 v[64:65], v[60:63], off sc1
	global_store_dwordx4 v[64:65], v[44:47], off offset:256 sc1
	v_cvt_pk_bf16_f32 v42, v48, v49
	v_cvt_pk_bf16_f32 v43, v50, v51
	v_lshl_add_u64 v[44:45], v[172:173], 0, v[40:41]
	v_cvt_pk_bf16_f32 v40, v52, v53
	v_cvt_pk_bf16_f32 v41, v54, v55
	v_lshlrev_b64 v[24:25], 11, v[24:25]
	v_ashrrev_i32_e32 v9, 31, v8
	v_cvt_pk_bf16_f32 v31, v26, v27
	global_store_dwordx4 v[44:45], v[40:43], off sc1
	global_store_dwordx4 v[44:45], v[28:31], off offset:256 sc1
	v_cvt_pk_bf16_f32 v26, v32, v33
	v_cvt_pk_bf16_f32 v27, v34, v35
	v_lshl_add_u64 v[28:29], v[172:173], 0, v[24:25]
	v_cvt_pk_bf16_f32 v24, v36, v37
	v_cvt_pk_bf16_f32 v25, v38, v39
	v_lshlrev_b64 v[8:9], 11, v[8:9]
	v_cvt_pk_bf16_f32 v15, v10, v11
	global_store_dwordx4 v[28:29], v[24:27], off sc1
	global_store_dwordx4 v[28:29], v[12:15], off offset:256 sc1
	v_cvt_pk_bf16_f32 v10, v16, v17
	v_cvt_pk_bf16_f32 v11, v18, v19
	v_lshl_add_u64 v[12:13], v[172:173], 0, v[8:9]
	v_cvt_pk_bf16_f32 v8, v20, v21
	v_cvt_pk_bf16_f32 v9, v22, v23
	v_cvt_pk_bf16_f32 v4, v4, v5
	v_cvt_pk_bf16_f32 v5, v6, v7
	v_cvt_pk_bf16_f32 v6, v0, v1
	v_cvt_pk_bf16_f32 v7, v2, v3
	global_store_dwordx4 v[12:13], v[8:11], off sc1
	global_store_dwordx4 v[12:13], v[4:7], off offset:256 sc1
	s_andn2_b64 vcc, exec, s[6:7]
	s_mov_b64 s[6:7], -1
	s_cbranch_vccnz .LBB0_1115
	s_andn2_b64 vcc, exec, s[0:1]
	s_cbranch_vccnz .LBB0_1114
	s_barrier
	s_branch .LBB0_1114

; __device__ __forceinline__ unsigned pk_bf16(float lo, float hi) { const f32x2 v = {lo, hi}; return __builtin_bit_cast(unsigned, __builtin_convertvector(v, b16x2)); }
;     __device__ __forceinline__ void row(int r, int col32, int fq, const f32x4& a00, const f32x4& a01, const f32x4& a10, const f32x4& a11) const { half(r, col32, fq, a00, a01); half(r, col32 + HALF, fq, a10, a11); }
;     __device__ __forceinline__ void row(int r, int col32, int fq, const f32x4& a00, const f32x4& a01, const f32x4& a10, const f32x4& a11) const { half(r, col32, fq, a00, a01); half(r, col32 + HALF, fq, a10, a11); }
; __device__ __forceinline__ void phase6(const Params& p) {
;     ...
;     for (int it = blockIdx.x; it < MS / 16; it += gridDim.x) {
;         const int row0 = it * 16 + (threadIdx.x >> 6) * 2;
;         f32x4 v[2][4], x[2][4];
; #pragma unroll
;         for (int r = 0; r < 2; ++r)
; #pragma unroll
;             for (int j = 0; j < 4; ++j) {
;                 { const u32x2 pb2 = *(const u32x2*)((const bf16_t*)(ws + O_P) + (size_t)(row0 + r) * D + 4 * lane + 256 * j);
;                   v[r][j] = (f32x4){__uint_as_float(pb2.x << 16), __uint_as_float(pb2.x & 0xffff0000u), __uint_as_float(pb2.y << 16), __uint_as_float(pb2.y & 0xffff0000u)}; }
;                 x[r][j] = *(const f32x4*)(p.in[0] + (size_t)(row0 + r) * D + 4 * lane + 256 * j);
;             }
; #pragma unroll
;         for (int r = 0; r < 2; ++r) {
;             const int row = row0 + r;
;             float ss = 0.f;
; #pragma unroll
;             for (int j = 0; j < 4; ++j) ss += (v[r][j][0] * v[r][j][0] + v[r][j][1] * v[r][j][1]) + (v[r][j][2] * v[r][j][2] + v[r][j][3] * v[r][j][3]);
;             const float rs = rsqrtf(wave_sum(ss) * (1.0f / D) + RMS_EPS);
;             float s2 = 0.f;
; #pragma unroll
;             for (int j = 0; j < 4; ++j) {
;                 v[r][j] = x[r][j] + v[r][j] * rs * g1[j];
;                 { u32x2 hb; hb.x = pk_bf16(v[r][j][0], v[r][j][1]); hb.y = pk_bf16(v[r][j][2], v[r][j][3]);
;                   *(u32x2*)((bf16_t*)(ws + O_H1B) + (size_t)row * D + 4 * lane + 256 * j) = hb;
;                   v[r][j] = (f32x4){__uint_as_float(hb.x << 16), __uint_as_float(hb.x & 0xffff0000u), __uint_as_float(hb.y << 16), __uint_as_float(hb.y & 0xffff0000u)}; }
.LBB0_1184:
	v_ashrrev_i32_e32 v49, 31, v48
	v_lshlrev_b64 v[54:55], 11, v[48:49]
	v_lshl_add_u64 v[32:33], v[40:41], 0, v[54:55]
	global_load_dwordx2 v[34:35], v[32:33], off offset:1536
	global_load_dwordx2 v[36:37], v[32:33], off
	global_load_dwordx2 v[38:39], v[32:33], off offset:512
	global_load_dwordx2 v[56:57], v[32:33], off offset:1024
	v_add_u32_e32 v32, 1, v48
	v_ashrrev_i32_e32 v33, 31, v32
	v_lshlrev_b64 v[52:53], 11, v[32:33]
	v_lshl_add_u64 v[58:59], v[40:41], 0, v[52:53]
	global_load_dwordx2 v[86:87], v[58:59], off offset:1536
	v_lshlrev_b64 v[60:61], 12, v[48:49]
	v_lshl_add_u64 v[60:61], v[46:47], 0, v[60:61]
	global_load_dwordx4 v[62:65], v[60:61], off
	global_load_dwordx4 v[66:69], v[60:61], off offset:1024
	global_load_dwordx4 v[70:73], v[60:61], off offset:2048
	global_load_dwordx4 v[82:85], v[60:61], off offset:3072
	global_load_dwordx2 v[106:107], v[58:59], off
	global_load_dwordx2 v[108:109], v[58:59], off offset:512
	global_load_dwordx2 v[110:111], v[58:59], off offset:1024
	v_lshlrev_b64 v[32:33], 12, v[32:33]
	s_add_i32 s7, s7, s92
	s_cmpk_lt_i32 s7, 0x800
	v_add_u32_e32 v48, s1, v48
	s_waitcnt vmcnt(11)
	v_lshlrev_b32_e32 v89, 16, v34
	s_waitcnt vmcnt(10)
	v_and_b32_e32 v95, 0xffff0000, v36
	v_and_b32_e32 v97, 0xffff0000, v37
	v_and_b32_e32 v91, 0xffff0000, v34
	v_lshlrev_b32_e32 v92, 16, v35
	v_and_b32_e32 v93, 0xffff0000, v35
	v_lshlrev_b32_e32 v94, 16, v36
	v_lshlrev_b32_e32 v96, 16, v37
	s_waitcnt vmcnt(9)
	v_lshlrev_b32_e32 v98, 16, v38
	v_and_b32_e32 v101, 0xffff0000, v39
	v_and_b32_e32 v100, 0xffff0000, v38
	v_mul_f32_e32 v34, v97, v97
	v_mul_f32_e32 v38, v95, v95
	v_mov_b32_e32 v35, v89
	v_lshlrev_b32_e32 v99, 16, v39
	s_waitcnt vmcnt(8)
	v_and_b32_e32 v103, 0xffff0000, v56
	v_and_b32_e32 v105, 0xffff0000, v57
	v_pk_mul_f32 v[36:37], v[100:101], v[100:101]
	v_pk_fma_f32 v[74:75], v[96:97], v[96:97], v[34:35] op_sel_hi:[1,1,0]
	v_pk_fma_f32 v[38:39], v[94:95], v[94:95], v[38:39] op_sel_hi:[1,1,0]
	v_lshlrev_b32_e32 v102, 16, v56
	v_lshlrev_b32_e32 v104, 16, v57
	v_mul_f32_e32 v56, v103, v103
	v_mul_f32_e32 v60, v105, v105
	v_pk_fma_f32 v[36:37], v[98:99], v[98:99], v[36:37]
	v_mov_b32_e32 v88, v38
	v_mov_b32_e32 v34, v74
	v_mul_f32_e32 v49, v91, v91
	v_mul_f32_e32 v81, v92, v92
	v_mul_f32_e32 v90, v93, v93
	v_pk_fma_f32 v[56:57], v[102:103], v[102:103], v[56:57] op_sel_hi:[1,1,0]
	v_pk_fma_f32 v[60:61], v[104:105], v[104:105], v[60:61] op_sel_hi:[1,1,0]
	v_pk_add_f32 v[38:39], v[38:39], v[74:75]
	v_pk_add_f32 v[36:37], v[36:37], v[36:37] op_sel:[0,1] op_sel_hi:[1,0]
	v_pk_mul_f32 v[34:35], v[88:89], v[34:35]
	v_mov_b32_e32 v57, v81
	v_mov_b32_e32 v61, v90
	v_mov_b32_e32 v37, v49
	v_mov_b32_e32 v39, v35
	v_pk_add_f32 v[56:57], v[56:57], v[60:61]
	v_pk_add_f32 v[34:35], v[38:39], v[36:37]
	s_waitcnt vmcnt(7)
	v_lshlrev_b32_e32 v59, 16, v86
	v_pk_add_f32 v[34:35], v[34:35], v[56:57]
	v_and_b32_e32 v61, 0xffff0000, v86
	v_add_f32_e32 v34, v34, v35
	ds_bpermute_b32 v35, v51, v34
	v_and_b32_e32 v57, 0xffff0000, v87
	v_mov_b32_e32 v86, v98
	v_mov_b32_e32 v90, v89
	v_mov_b32_e32 v115, v59
	s_waitcnt lgkmcnt(0)
	v_add_f32_e32 v34, v34, v35
	ds_bpermute_b32 v35, v76, v34
	s_waitcnt vmcnt(0)
	v_and_b32_e32 v113, 0xffff0000, v110
	v_lshlrev_b32_e32 v112, 16, v110
	v_lshlrev_b32_e32 v110, 16, v111
	v_and_b32_e32 v111, 0xffff0000, v111
	s_waitcnt lgkmcnt(0)
	v_add_f32_e32 v34, v34, v35
	ds_bpermute_b32 v35, v77, v34
	v_mul_f32_e32 v81, v57, v57
	v_lshl_add_u64 v[74:75], v[46:47], 0, v[32:33]
	s_waitcnt lgkmcnt(0)
	v_add_f32_e32 v34, v34, v35
	ds_bpermute_b32 v35, v78, v34
	s_waitcnt lgkmcnt(0)
	v_add_f32_e32 v49, v34, v35
	ds_bpermute_b32 v56, v79, v49
	global_load_dwordx4 v[36:39], v[74:75], off
	global_load_dwordx4 v[32:35], v[74:75], off offset:1024
	s_waitcnt lgkmcnt(0)
	v_add_f32_e32 v49, v49, v56
	ds_bpermute_b32 v58, v80, v49
	v_lshlrev_b32_e32 v56, 16, v87
	v_mov_b32_e32 v87, v100
	v_mov_b32_e32 v100, v99
	v_mul_f32_e32 v60, v56, v56
	s_waitcnt lgkmcnt(0)
	v_add_f32_e32 v49, v49, v58
	v_fmamk_f32 v49, v49, 0x3a800000, v50
	v_mul_f32_e32 v58, 0x4b800000, v49
	v_cmp_gt_f32_e32 vcc, s6, v49
	s_nop 1
	v_cndmask_b32_e32 v49, v49, v58, vcc
	v_rsq_f32_e32 v49, v49
	s_nop 0
	v_mul_f32_e32 v58, 0x45800000, v49
	v_cndmask_b32_e32 v58, v49, v58, vcc
	v_pk_mul_f32 v[88:89], v[58:59], v[94:95] op_sel_hi:[0,1]
	v_pk_mul_f32 v[94:95], v[58:59], v[96:97] op_sel_hi:[0,1]
	v_pk_mul_f32 v[86:87], v[58:59], v[86:87] op_sel_hi:[0,1]
	v_pk_mul_f32 v[96:97], v[58:59], v[100:101] op_sel_hi:[0,1]
	v_pk_mul_f32 v[90:91], v[58:59], v[90:91] op_sel_hi:[0,1]
	v_pk_mul_f32 v[92:93], v[58:59], v[92:93] op_sel_hi:[0,1]
	v_pk_fma_f32 v[64:65], v[2:3], v[94:95], v[64:65]
	v_pk_fma_f32 v[62:63], v[0:1], v[88:89], v[62:63]
	v_pk_fma_f32 v[68:69], v[6:7], v[96:97], v[68:69]
	v_pk_fma_f32 v[66:67], v[4:5], v[86:87], v[66:67]
	v_pk_mul_f32 v[98:99], v[58:59], v[102:103] op_sel_hi:[0,1]
	v_pk_mul_f32 v[100:101], v[58:59], v[104:105] op_sel_hi:[0,1]
	v_pk_fma_f32 v[84:85], v[14:15], v[92:93], v[84:85]
	v_pk_fma_f32 v[82:83], v[12:13], v[90:91], v[82:83]
	v_cvt_pk_bf16_f32 v90, v62, v63
	v_cvt_pk_bf16_f32 v91, v64, v65
	v_cvt_pk_bf16_f32 v92, v66, v67
	v_cvt_pk_bf16_f32 v93, v68, v69
	v_pk_fma_f32 v[72:73], v[10:11], v[100:101], v[72:73]
	v_pk_fma_f32 v[70:71], v[8:9], v[98:99], v[70:71]
	v_and_b32_e32 v99, 0xffff0000, v91
	v_and_b32_e32 v101, 0xffff0000, v90
	v_and_b32_e32 v63, 0xffff0000, v93
	v_and_b32_e32 v67, 0xffff0000, v92
	v_cvt_pk_bf16_f32 v94, v70, v71
	v_cvt_pk_bf16_f32 v96, v82, v83
	v_lshlrev_b32_e32 v98, 16, v91
	v_lshlrev_b32_e32 v100, 16, v90
	v_lshlrev_b32_e32 v62, 16, v93
	v_lshlrev_b32_e32 v66, 16, v92
	v_mov_b32_e32 v70, v101
; __device__ __forceinline__ unsigned pk_bf16(float lo, float hi) { const f32x2 v = {lo, hi}; return __builtin_bit_cast(unsigned, __builtin_convertvector(v, b16x2)); }
;     __device__ __forceinline__ void row(int r, int col32, int fq, const f32x4& a00, const f32x4& a01, const f32x4& a10, const f32x4& a11) const { half(r, col32, fq, a00, a01); half(r, col32 + HALF, fq, a10, a11); }
;     __device__ __forceinline__ void row(int r, int col32, int fq, const f32x4& a00, const f32x4& a01, const f32x4& a10, const f32x4& a11) const { half(r, col32, fq, a00, a01); half(r, col32 + HALF, fq, a10, a11); }
;     __device__ __forceinline__ void row(int r, int col32, int fq, const f32x4& a00, const f32x4& a01, const f32x4& a10, const f32x4& a11) const { half(r, col32, fq, a00, a01); half(r, col32 + HALF, fq, a10, a11); }
; __device__ __forceinline__ void phase6(const Params& p) {
;     ...
;         for (int r = 0; r < 2; ++r) {
;             const int row = row0 + r;
;             float ss = 0.f;
; #pragma unroll
;             for (int j = 0; j < 4; ++j) ss += (v[r][j][0] * v[r][j][0] + v[r][j][1] * v[r][j][1]) + (v[r][j][2] * v[r][j][2] + v[r][j][3] * v[r][j][3]);
;             const float rs = rsqrtf(wave_sum(ss) * (1.0f / D) + RMS_EPS);
;             float s2 = 0.f;
; #pragma unroll
;             for (int j = 0; j < 4; ++j) {
;                 v[r][j] = x[r][j] + v[r][j] * rs * g1[j];
;                 { u32x2 hb; hb.x = pk_bf16(v[r][j][0], v[r][j][1]); hb.y = pk_bf16(v[r][j][2], v[r][j][3]);
;                   *(u32x2*)((bf16_t*)(ws + O_H1B) + (size_t)row * D + 4 * lane + 256 * j) = hb;
;                   v[r][j] = (f32x4){__uint_as_float(hb.x << 16), __uint_as_float(hb.x & 0xffff0000u), __uint_as_float(hb.y << 16), __uint_as_float(hb.y & 0xffff0000u)}; }
;                 s2 += (v[r][j][0] * v[r][j][0] + v[r][j][1] * v[r][j][1]) + (v[r][j][2] * v[r][j][2] + v[r][j][3] * v[r][j][3]);
;             }
;             const float rs2 = rsqrtf(wave_sum(s2) * (1.0f / D) + RMS_EPS);
;             bf16_t* fr_ = (bf16_t*)(ws + O_F) + (size_t)row * D;
; #pragma unroll
;             for (int j = 0; j < 4; ++j) {
;                 u32x2 w; w.x = pk_bf16(v[r][j][0] * rs2 * g2[j][0], v[r][j][1] * rs2 * g2[j][1]); w.y = pk_bf16(v[r][j][2] * rs2 * g2[j][2], v[r][j][3] * rs2 * g2[j][3]);
;                 *(u32x2*)(fr_ + 4 * lane + 256 * j) = w;
	v_mov_b32_e32 v71, v99
	v_mov_b32_e32 v82, v67
	v_mov_b32_e32 v83, v63
	v_cvt_pk_bf16_f32 v95, v72, v73
	v_mov_b32_e32 v68, v100
	v_mov_b32_e32 v69, v98
	v_mov_b32_e32 v72, v66
	v_mov_b32_e32 v73, v62
	v_pk_mul_f32 v[70:71], v[70:71], v[70:71]
	v_pk_mul_f32 v[82:83], v[82:83], v[82:83]
	v_lshlrev_b32_e32 v64, 16, v95
	v_pk_fma_f32 v[68:69], v[68:69], v[68:69], v[70:71]
	v_pk_fma_f32 v[70:71], v[72:73], v[72:73], v[82:83]
	v_cvt_pk_bf16_f32 v97, v84, v85
	v_and_b32_e32 v65, 0xffff0000, v95
	v_mul_f32_e32 v58, v64, v64
	v_pk_add_f32 v[86:87], v[70:71], v[70:71] op_sel_hi:[0,1]
	v_lshlrev_b32_e32 v70, 16, v94
	v_pk_fma_f32 v[84:85], v[64:65], v[64:65], v[58:59] op_sel_hi:[1,1,0]
	v_pk_add_f32 v[82:83], v[68:69], v[68:69] op_sel_hi:[0,1]
	v_and_b32_e32 v71, 0xffff0000, v94
	v_mul_f32_e32 v58, v70, v70
	v_lshlrev_b32_e32 v68, 16, v97
	v_and_b32_e32 v69, 0xffff0000, v97
	v_lshlrev_b32_e32 v72, 16, v96
	v_and_b32_e32 v73, 0xffff0000, v96
	v_pk_fma_f32 v[88:89], v[70:71], v[70:71], v[58:59] op_sel_hi:[1,1,0]
	v_pk_mul_f32 v[102:103], v[68:69], v[68:69]
	v_pk_mul_f32 v[104:105], v[72:73], v[72:73]
	v_mov_b32_e32 v82, v102
	v_mov_b32_e32 v86, v103
	v_mov_b32_e32 v88, v104
	v_mov_b32_e32 v84, v105
	v_and_b32_e32 v105, 0xffff0000, v107
	v_pk_add_f32 v[82:83], v[82:83], v[86:87]
	v_pk_add_f32 v[84:85], v[88:89], v[84:85]
	v_and_b32_e32 v103, 0xffff0000, v106
	v_lshlrev_b32_e32 v104, 16, v107
	v_mul_f32_e32 v58, v105, v105
	v_pk_add_f32 v[82:83], v[84:85], v[82:83]
	v_lshlrev_b32_e32 v102, 16, v106
	v_pk_fma_f32 v[84:85], v[104:105], v[104:105], v[58:59] op_sel_hi:[1,1,0]
	v_lshlrev_b32_e32 v107, 16, v109
	v_lshlrev_b32_e32 v106, 16, v108
	v_and_b32_e32 v109, 0xffff0000, v109
	v_and_b32_e32 v108, 0xffff0000, v108
	v_mul_f32_e32 v58, v103, v103
	v_pk_mul_f32 v[86:87], v[108:109], v[108:109]
	v_pk_fma_f32 v[88:89], v[102:103], v[102:103], v[58:59] op_sel_hi:[1,1,0]
	v_pk_fma_f32 v[86:87], v[106:107], v[106:107], v[86:87]
	v_mov_b32_e32 v58, v88
	v_mov_b32_e32 v114, v84
	v_mul_f32_e32 v49, v61, v61
	v_pk_add_f32 v[84:85], v[88:89], v[84:85]
	v_pk_mul_f32 v[88:89], v[58:59], v[114:115]
	v_pk_add_f32 v[86:87], v[86:87], v[86:87] op_sel:[0,1] op_sel_hi:[1,0]
	v_mov_b32_e32 v85, v89
	v_mov_b32_e32 v87, v49
	v_mul_f32_e32 v58, v113, v113
	v_pk_add_f32 v[84:85], v[84:85], v[86:87]
	v_pk_fma_f32 v[86:87], v[112:113], v[112:113], v[58:59] op_sel_hi:[1,1,0]
	v_mul_f32_e32 v58, v111, v111
	v_pk_fma_f32 v[88:89], v[110:111], v[110:111], v[58:59] op_sel_hi:[1,1,0]
	v_mov_b32_e32 v87, v60
	v_mov_b32_e32 v89, v81
	v_pk_add_f32 v[86:87], v[86:87], v[88:89]
	s_nop 0
	v_pk_add_f32 v[84:85], v[84:85], v[86:87]
	v_mov_b32_e32 v87, v82
	v_mov_b32_e32 v86, v84
	v_mov_b32_e32 v82, v85
	v_pk_add_f32 v[86:87], v[86:87], v[82:83]
	ds_bpermute_b32 v89, v51, v87
	ds_bpermute_b32 v88, v51, v86
	global_load_dwordx4 v[82:85], v[74:75], off offset:2048
	s_waitcnt lgkmcnt(0)
	v_pk_add_f32 v[114:115], v[86:87], v[88:89]
	global_load_dwordx4 v[86:89], v[74:75], off offset:3072
	ds_bpermute_b32 v117, v76, v115
	ds_bpermute_b32 v116, v76, v114
	s_waitcnt lgkmcnt(0)
	v_pk_add_f32 v[74:75], v[114:115], v[116:117]
	ds_bpermute_b32 v115, v77, v75
	ds_bpermute_b32 v114, v77, v74
	v_lshl_add_u64 v[116:117], v[42:43], 0, v[54:55]
	global_store_dwordx2 v[116:117], v[90:91], off sc1
	global_store_dwordx2 v[116:117], v[92:93], off offset:512 sc1
	v_lshl_add_u64 v[54:55], v[44:45], 0, v[54:55]
	global_store_dwordx2 v[116:117], v[94:95], off offset:1024 sc1
	global_store_dwordx2 v[116:117], v[96:97], off offset:1536 sc1
	s_waitcnt lgkmcnt(0)
	v_pk_add_f32 v[74:75], v[74:75], v[114:115]
	ds_bpermute_b32 v115, v78, v75
	ds_bpermute_b32 v114, v78, v74
	s_waitcnt lgkmcnt(0)
	v_pk_add_f32 v[74:75], v[74:75], v[114:115]
	ds_bpermute_b32 v115, v79, v75
	ds_bpermute_b32 v114, v79, v74
	s_waitcnt lgkmcnt(0)
	v_pk_add_f32 v[74:75], v[74:75], v[114:115]
	ds_bpermute_b32 v115, v80, v75
	ds_bpermute_b32 v114, v80, v74
	s_waitcnt lgkmcnt(0)
	v_pk_add_f32 v[74:75], v[74:75], v[114:115]
	s_nop 0
	v_pk_fma_f32 v[74:75], v[74:75], s[0:1], v[50:51] op_sel_hi:[1,0,0]
	s_nop 0
	v_mul_f32_e32 v49, 0x4b800000, v75
	v_cmp_gt_f32_e32 vcc, s6, v75
	s_nop 1
	v_cndmask_b32_e32 v49, v75, v49, vcc
	v_rsq_f32_e32 v49, v49
	s_nop 0
	v_mul_f32_e32 v58, 0x45800000, v49
	v_cndmask_b32_e32 v58, v49, v58, vcc
	v_mul_f32_e32 v49, 0x4b800000, v74
	v_cmp_gt_f32_e32 vcc, s6, v74
	v_pk_mul_f32 v[90:91], v[58:59], v[100:101] op_sel_hi:[0,1]
	v_pk_mul_f32 v[92:93], v[58:59], v[98:99] op_sel_hi:[0,1]
	v_cndmask_b32_e32 v49, v74, v49, vcc
	v_rsq_f32_e32 v49, v49
	v_pk_mul_f32 v[90:91], v[28:29], v[90:91]
	v_pk_mul_f32 v[74:75], v[30:31], v[92:93]
	v_cvt_pk_bf16_f32 v90, v90, v91
	v_mul_f32_e32 v60, 0x45800000, v49
	v_cvt_pk_bf16_f32 v91, v74, v75
	v_cndmask_b32_e32 v74, v49, v60, vcc
	global_store_dwordx2 v[54:55], v[90:91], off sc1
	v_pk_mul_f32 v[90:91], v[74:75], v[102:103] op_sel_hi:[0,1]
	v_pk_mul_f32 v[92:93], v[74:75], v[104:105] op_sel_hi:[0,1]
	s_waitcnt vmcnt(8)
	v_pk_fma_f32 v[38:39], v[2:3], v[92:93], v[38:39]
	v_pk_fma_f32 v[36:37], v[0:1], v[90:91], v[36:37]
	v_mov_b32_e32 v60, v59
	v_cvt_pk_bf16_f32 v36, v36, v37
	v_cvt_pk_bf16_f32 v37, v38, v39
	v_mov_b32_e32 v38, v106
	v_mov_b32_e32 v39, v108
	v_mov_b32_e32 v108, v107
	v_pk_mul_f32 v[38:39], v[74:75], v[38:39] op_sel_hi:[0,1]
	v_pk_mul_f32 v[90:91], v[74:75], v[108:109] op_sel_hi:[0,1]
	s_waitcnt vmcnt(7)
	v_pk_fma_f32 v[34:35], v[6:7], v[90:91], v[34:35]
	v_pk_fma_f32 v[32:33], v[4:5], v[38:39], v[32:33]
	v_pk_mul_f32 v[38:39], v[74:75], v[110:111] op_sel_hi:[0,1]
	v_cvt_pk_bf16_f32 v32, v32, v33
	v_cvt_pk_bf16_f32 v33, v34, v35
	v_pk_mul_f32 v[34:35], v[74:75], v[112:113] op_sel_hi:[0,1]
	s_waitcnt vmcnt(6)
; __device__ __forceinline__ unsigned pk_bf16(float lo, float hi) { const f32x2 v = {lo, hi}; return __builtin_bit_cast(unsigned, __builtin_convertvector(v, b16x2)); }
;     __device__ __forceinline__ void row(int r, int col32, int fq, const f32x4& a00, const f32x4& a01, const f32x4& a10, const f32x4& a11) const { half(r, col32, fq, a00, a01); half(r, col32 + HALF, fq, a10, a11); }
;     __device__ __forceinline__ void row(int r, int col32, int fq, const f32x4& a00, const f32x4& a01, const f32x4& a10, const f32x4& a11) const { half(r, col32, fq, a00, a01); half(r, col32 + HALF, fq, a10, a11); }
;     __device__ __forceinline__ void row(int r, int col32, int fq, const f32x4& a00, const f32x4& a01, const f32x4& a10, const f32x4& a11) const { half(r, col32, fq, a00, a01); half(r, col32 + HALF, fq, a10, a11); }
; __device__ __forceinline__ void phase6(const Params& p) {
;     ...
;         for (int r = 0; r < 2; ++r) {
;             const int row = row0 + r;
;             float ss = 0.f;
; #pragma unroll
;             for (int j = 0; j < 4; ++j) ss += (v[r][j][0] * v[r][j][0] + v[r][j][1] * v[r][j][1]) + (v[r][j][2] * v[r][j][2] + v[r][j][3] * v[r][j][3]);
;             const float rs = rsqrtf(wave_sum(ss) * (1.0f / D) + RMS_EPS);
;             float s2 = 0.f;
; #pragma unroll
;             for (int j = 0; j < 4; ++j) {
;                 v[r][j] = x[r][j] + v[r][j] * rs * g1[j];
;                 { u32x2 hb; hb.x = pk_bf16(v[r][j][0], v[r][j][1]); hb.y = pk_bf16(v[r][j][2], v[r][j][3]);
;                   *(u32x2*)((bf16_t*)(ws + O_H1B) + (size_t)row * D + 4 * lane + 256 * j) = hb;
;                   v[r][j] = (f32x4){__uint_as_float(hb.x << 16), __uint_as_float(hb.x & 0xffff0000u), __uint_as_float(hb.y << 16), __uint_as_float(hb.y & 0xffff0000u)}; }
;                 s2 += (v[r][j][0] * v[r][j][0] + v[r][j][1] * v[r][j][1]) + (v[r][j][2] * v[r][j][2] + v[r][j][3] * v[r][j][3]);
;             }
;             const float rs2 = rsqrtf(wave_sum(s2) * (1.0f / D) + RMS_EPS);
;             bf16_t* fr_ = (bf16_t*)(ws + O_F) + (size_t)row * D;
; #pragma unroll
;             for (int j = 0; j < 4; ++j) {
;                 u32x2 w; w.x = pk_bf16(v[r][j][0] * rs2 * g2[j][0], v[r][j][1] * rs2 * g2[j][1]); w.y = pk_bf16(v[r][j][2] * rs2 * g2[j][2], v[r][j][3] * rs2 * g2[j][3]);
;                 *(u32x2*)(fr_ + 4 * lane + 256 * j) = w;
;             }
;         }
	v_pk_fma_f32 v[38:39], v[10:11], v[38:39], v[84:85]
	v_pk_fma_f32 v[34:35], v[8:9], v[34:35], v[82:83]
	v_pk_mul_f32 v[56:57], v[74:75], v[56:57] op_sel_hi:[0,1]
	v_cvt_pk_bf16_f32 v34, v34, v35
	v_cvt_pk_bf16_f32 v35, v38, v39
	v_pk_mul_f32 v[38:39], v[74:75], v[60:61] op_sel_hi:[0,1]
	s_waitcnt vmcnt(5)
	v_pk_fma_f32 v[56:57], v[14:15], v[56:57], v[88:89]
	v_pk_fma_f32 v[38:39], v[12:13], v[38:39], v[86:87]
	v_and_b32_e32 v61, 0xffff0000, v36
	v_cvt_pk_bf16_f32 v38, v38, v39
	v_cvt_pk_bf16_f32 v39, v56, v57
	v_and_b32_e32 v57, 0xffff0000, v37
	v_lshlrev_b32_e32 v56, 16, v37
	v_lshlrev_b32_e32 v60, 16, v36
	v_mov_b32_e32 v82, v61
	v_mov_b32_e32 v83, v57
	v_mov_b32_e32 v74, v60
	v_mov_b32_e32 v75, v56
	v_pk_mul_f32 v[82:83], v[82:83], v[82:83]
	v_and_b32_e32 v85, 0xffff0000, v32
	v_pk_fma_f32 v[74:75], v[74:75], v[74:75], v[82:83]
	v_and_b32_e32 v83, 0xffff0000, v33
	v_lshlrev_b32_e32 v82, 16, v33
	v_lshlrev_b32_e32 v84, 16, v32
	v_mov_b32_e32 v88, v85
	v_mov_b32_e32 v89, v83
	v_mov_b32_e32 v86, v84
	v_mov_b32_e32 v87, v82
	v_pk_mul_f32 v[88:89], v[88:89], v[88:89]
	v_pk_add_f32 v[74:75], v[74:75], v[74:75] op_sel_hi:[0,1]
	v_pk_fma_f32 v[86:87], v[86:87], v[86:87], v[88:89]
	v_lshlrev_b32_e32 v88, 16, v35
	v_and_b32_e32 v89, 0xffff0000, v35
	v_mul_f32_e32 v74, v88, v88
	v_lshlrev_b32_e32 v92, 16, v34
	v_pk_fma_f32 v[90:91], v[88:89], v[88:89], v[74:75] op_sel_hi:[1,1,0]
	v_and_b32_e32 v93, 0xffff0000, v34
	v_mul_f32_e32 v74, v92, v92
	v_lshlrev_b32_e32 v96, 16, v39
	v_and_b32_e32 v97, 0xffff0000, v39
	v_lshlrev_b32_e32 v100, 16, v38
	v_and_b32_e32 v101, 0xffff0000, v38
	v_pk_add_f32 v[86:87], v[86:87], v[86:87] op_sel_hi:[0,1]
	v_pk_fma_f32 v[94:95], v[92:93], v[92:93], v[74:75] op_sel_hi:[1,1,0]
	v_pk_mul_f32 v[98:99], v[96:97], v[96:97]
	v_pk_mul_f32 v[102:103], v[100:101], v[100:101]
	v_mov_b32_e32 v74, v98
	v_mov_b32_e32 v86, v99
	v_mov_b32_e32 v94, v102
	v_mov_b32_e32 v90, v103
	v_pk_add_f32 v[74:75], v[74:75], v[86:87]
	v_pk_add_f32 v[86:87], v[94:95], v[90:91]
	s_nop 0
	v_pk_add_f32 v[74:75], v[86:87], v[74:75]
	s_nop 0
	v_add_f32_e32 v49, v74, v75
	ds_bpermute_b32 v59, v51, v49
	s_waitcnt lgkmcnt(0)
	v_add_f32_e32 v49, v49, v59
	v_pk_mul_f32 v[66:67], v[58:59], v[66:67] op_sel_hi:[0,1]
	v_pk_mul_f32 v[62:63], v[58:59], v[62:63] op_sel_hi:[0,1]
	ds_bpermute_b32 v59, v76, v49
	v_pk_mul_f32 v[66:67], v[24:25], v[66:67]
	v_pk_mul_f32 v[62:63], v[26:27], v[62:63]
	v_cvt_pk_bf16_f32 v66, v66, v67
	v_cvt_pk_bf16_f32 v67, v62, v63
	s_waitcnt lgkmcnt(0)
	v_add_f32_e32 v49, v49, v59
	v_pk_mul_f32 v[62:63], v[58:59], v[70:71] op_sel_hi:[0,1]
	ds_bpermute_b32 v59, v77, v49
	v_pk_mul_f32 v[62:63], v[20:21], v[62:63]
	global_store_dwordx2 v[54:55], v[66:67], off offset:512 sc1
	v_cvt_pk_bf16_f32 v62, v62, v63
	s_waitcnt lgkmcnt(0)
	v_add_f32_e32 v49, v49, v59
	v_pk_mul_f32 v[64:65], v[58:59], v[64:65] op_sel_hi:[0,1]
	ds_bpermute_b32 v59, v78, v49
	v_pk_mul_f32 v[64:65], v[22:23], v[64:65]
	s_waitcnt lgkmcnt(0)
	v_add_f32_e32 v49, v49, v59
	v_cvt_pk_bf16_f32 v63, v64, v65
	ds_bpermute_b32 v64, v79, v49
	global_store_dwordx2 v[54:55], v[62:63], off offset:1024 sc1
	v_pk_mul_f32 v[62:63], v[58:59], v[72:73] op_sel_hi:[0,1]
	v_pk_mul_f32 v[58:59], v[58:59], v[68:69] op_sel_hi:[0,1]
	v_pk_mul_f32 v[62:63], v[16:17], v[62:63]
	v_pk_mul_f32 v[58:59], v[18:19], v[58:59]
	s_waitcnt lgkmcnt(0)
	v_add_f32_e32 v49, v49, v64
	v_cvt_pk_bf16_f32 v62, v62, v63
	v_cvt_pk_bf16_f32 v63, v58, v59
	ds_bpermute_b32 v58, v80, v49
	global_store_dwordx2 v[54:55], v[62:63], off offset:1536 sc1
	v_lshl_add_u64 v[54:55], v[42:43], 0, v[52:53]
	global_store_dwordx2 v[54:55], v[36:37], off sc1
	global_store_dwordx2 v[54:55], v[32:33], off offset:512 sc1
	global_store_dwordx2 v[54:55], v[34:35], off offset:1024 sc1
	global_store_dwordx2 v[54:55], v[38:39], off offset:1536 sc1
	s_waitcnt lgkmcnt(0)
	v_add_f32_e32 v32, v49, v58
	v_fmamk_f32 v32, v32, 0x3a800000, v50
	v_mul_f32_e32 v33, 0x4b800000, v32
	v_cmp_gt_f32_e32 vcc, s6, v32
	s_nop 1
	v_cndmask_b32_e32 v32, v32, v33, vcc
	v_rsq_f32_e32 v36, v32
	v_lshl_add_u64 v[32:33], v[44:45], 0, v[52:53]
	v_mul_f32_e32 v34, 0x45800000, v36
	v_cndmask_b32_e32 v34, v36, v34, vcc
	v_pk_mul_f32 v[36:37], v[34:35], v[60:61] op_sel_hi:[0,1]
	v_pk_mul_f32 v[38:39], v[34:35], v[56:57] op_sel_hi:[0,1]
	v_pk_mul_f32 v[36:37], v[28:29], v[36:37]
	v_pk_mul_f32 v[38:39], v[30:31], v[38:39]
	v_cvt_pk_bf16_f32 v36, v36, v37
	v_cvt_pk_bf16_f32 v37, v38, v39
	global_store_dwordx2 v[32:33], v[36:37], off sc1
	v_pk_mul_f32 v[36:37], v[34:35], v[84:85] op_sel_hi:[0,1]
	v_pk_mul_f32 v[38:39], v[34:35], v[82:83] op_sel_hi:[0,1]
	v_pk_mul_f32 v[36:37], v[24:25], v[36:37]
	v_pk_mul_f32 v[38:39], v[26:27], v[38:39]
	v_cvt_pk_bf16_f32 v36, v36, v37
	v_cvt_pk_bf16_f32 v37, v38, v39
	global_store_dwordx2 v[32:33], v[36:37], off offset:512 sc1
	v_pk_mul_f32 v[36:37], v[34:35], v[92:93] op_sel_hi:[0,1]
	v_pk_mul_f32 v[38:39], v[34:35], v[88:89] op_sel_hi:[0,1]
	v_pk_mul_f32 v[36:37], v[20:21], v[36:37]
	v_pk_mul_f32 v[38:39], v[22:23], v[38:39]
	v_cvt_pk_bf16_f32 v36, v36, v37
	v_cvt_pk_bf16_f32 v37, v38, v39
	global_store_dwordx2 v[32:33], v[36:37], off offset:1024 sc1
	v_pk_mul_f32 v[36:37], v[34:35], v[100:101] op_sel_hi:[0,1]
	v_pk_mul_f32 v[34:35], v[34:35], v[96:97] op_sel_hi:[0,1]
	v_pk_mul_f32 v[36:37], v[16:17], v[36:37]
	v_pk_mul_f32 v[34:35], v[18:19], v[34:35]
	v_cvt_pk_bf16_f32 v36, v36, v37
	v_cvt_pk_bf16_f32 v37, v34, v35
	global_store_dwordx2 v[32:33], v[36:37], off offset:1536 sc1
	s_cbranch_scc1 .LBB0_1184
